# v33 plus attention-B epilogue de-serialised: 8 stash read-back loads and 8 gate loads issued up front with counted vmcnt
# speedup vs baseline: 1.0111x; 1.0002x over previous
; #define WBAR(n) do { asm volatile("s_waitcnt vmcnt(" #n ") lgkmcnt(0)" ::: "memory"); __builtin_amdgcn_s_barrier(); asm volatile("" ::: "memory"); } while (0)
; #define TRB(T, D0, vo_, vt_) do { T[0] = tr_read<v_rd_off(D0, 0, 0)>(vo_); T[1] = tr_read<v_rd_off(D0, 0, 1)>(vo_); T[2] = tr_read<v_rd_off(D0, 1, 0)>(vo_); T[3] = tr_read<v_rd_off(D0, 1, 1)>(vo_); \
;     T[4] = tr_read<v_rd_off(D0, 0, 0)>(vt_); T[5] = tr_read<v_rd_off(D0, 0, 1)>(vt_); T[6] = tr_read<v_rd_off(D0, 1, 0)>(vt_); T[7] = tr_read<v_rd_off(D0, 1, 1)>(vt_); } while (0)
; #define TRW(T, n) asm volatile("s_waitcnt lgkmcnt(" #n ")" : "+v"(T[0]), "+v"(T[1]), "+v"(T[2]), "+v"(T[3]), "+v"(T[4]), "+v"(T[5]), "+v"(T[6]), "+v"(T[7]) :: "memory")
; #define MB(od, T, o0, o1, t0, t1) do { od = __builtin_amdgcn_mfma_f32_32x32x16_bf16(o0, PKV(T[0], T[1]), od, 0, 0, 0); od = __builtin_amdgcn_mfma_f32_32x32x16_bf16(o1, PKV(T[2], T[3]), od, 0, 0, 0); \
;     od = __builtin_amdgcn_mfma_f32_32x32x16_bf16(t0, PKV(T[4], T[5]), od, 0, 0, 0); od = __builtin_amdgcn_mfma_f32_32x32x16_bf16(t1, PKV(T[6], T[7]), od, 0, 0, 0); } while (0)
; #define WBAR(n) do { asm volatile("s_waitcnt vmcnt(" #n ") lgkmcnt(0)" ::: "memory"); __builtin_amdgcn_s_barrier(); asm volatile("" ::: "memory"); } while (0)
; #define TRW(T, n) asm volatile("s_waitcnt lgkmcnt(" #n ")" : "+v"(T[0]), "+v"(T[1]), "+v"(T[2]), "+v"(T[3]), "+v"(T[4]), "+v"(T[5]), "+v"(T[6]), "+v"(T[7]) :: "memory")
; template <int LD> ...
;     ...
;   STEP(1, pB, ownA0, ownA1, ownB0, ownB1);
;   WBAR(0);
;   { const int vo_ = vbo + v1, vt_ = vbt + v1;
;     ot0 = lds_rd128<16384>(pxra); ot1 = lds_rd128<16384 + 1024>(pxra);
;     TRB(trA, 0, vo_, vt_);
;     asm volatile("s_waitcnt lgkmcnt(0)" : "+v"(ot0), "+v"(ot1) :: "memory"); TRW(trA, 0); TRB(trB, 1, vo_, vt_);
;     MB(o[0], trA, ownB0, ownB1, ot0, ot1); TRW(trB, 0); TRB(trA, 2, vo_, vt_);
;     MB(o[1], trB, ownB0, ownB1, ot0, ot1); TRW(trA, 0); TRB(trB, 3, vo_, vt_);
;     MB(o[2], trA, ownB0, ownB1, ot0, ot1); TRW(trB, 0);
;     MB(o[3], trB, ownB0, ownB1, ot0, ot1); }
.Lb_loop_done:
	ds_read_b128 v[84:87], v171 offset:0
	ds_read_b128 v[80:83], v171 offset:0x400
	v_add_u32_e32 v179, s25, v217
	ds_read_b64_tr_b16 v[88:89], v179 offset:0
	ds_read_b64_tr_b16 v[90:91], v179 offset:0x800
	ds_read_b64_tr_b16 v[92:93], v179 offset:0x1000
	ds_read_b64_tr_b16 v[94:95], v179 offset:0x1800
	v_add_u32_e32 v151, s25, v151
	ds_read_b64_tr_b16 v[136:137], v151 offset:0
	ds_read_b64_tr_b16 v[138:139], v151 offset:0x800
	ds_read_b64_tr_b16 v[140:141], v151 offset:0x1000
	ds_read_b64_tr_b16 v[142:143], v151 offset:0x1800
	v_xad_u32 v180, v172, v178, v173
	ds_read_b128 v[144:147], v180 offset:0x4000
	v_xad_u32 v174, v172, v174, v173
	ds_read_b128 v[152:155], v174 offset:0x4000
	v_xad_u32 v175, v172, v175, v173
	ds_read_b128 v[156:159], v175 offset:0x4000
	v_xad_u32 v172, v172, v176, v173
	ds_read_b128 v[166:169], v172 offset:0x4000
	s_waitcnt lgkmcnt(3)
	s_waitcnt lgkmcnt(2)
	s_waitcnt lgkmcnt(1)
	v_cmp_gt_u32_e32 vcc, 32, v150
	v_mfma_f32_32x32x16_bf16 v[64:79], v[144:147], v[120:123], v[64:79]
	s_waitcnt lgkmcnt(0)
	s_waitcnt lgkmcnt(0)
	v_mfma_f32_32x32x16_bf16 v[64:79], v[152:155], v[124:127], v[64:79]
	v_mfma_f32_32x32x16_bf16 v[64:79], v[156:159], v[112:115], v[64:79]
	v_mfma_f32_32x32x16_bf16 v[48:63], v[128:131], v[88:91], v[48:63]
	v_xor_b32_e32 v180, 0x80, v180
	ds_read_b128 v[88:91], v180 offset:0x4000
	v_xor_b32_e32 v180, 0x80, v180
	v_xor_b32_e32 v174, 0x80, v174
	ds_read_b128 v[120:123], v174 offset:0x4000
	v_xor_b32_e32 v174, 0x80, v174
	v_xor_b32_e32 v175, 0x80, v175
	ds_read_b128 v[112:115], v175 offset:0x4000
	v_xor_b32_e32 v175, 0x80, v175
	v_xor_b32_e32 v172, 0x80, v172
	ds_read_b128 v[124:127], v172 offset:0x4000
	v_xor_b32_e32 v172, 0x80, v172
	ds_read_b64_tr_b16 v[144:145], v179 offset:0x200
	ds_read_b64_tr_b16 v[146:147], v179 offset:0xa00
	ds_read_b64_tr_b16 v[152:153], v179 offset:0x1200
	ds_read_b64_tr_b16 v[154:155], v179 offset:0x1a00
	v_mfma_f32_32x32x16_bf16 v[64:79], v[166:169], v[100:103], v[64:79]
	ds_read_b64_tr_b16 v[156:157], v151 offset:0x200
	ds_read_b64_tr_b16 v[158:159], v151 offset:0xa00
	ds_read_b64_tr_b16 v[100:101], v151 offset:0x1200
	ds_read_b64_tr_b16 v[102:103], v151 offset:0x1a00
	s_waitcnt lgkmcnt(11)
	s_waitcnt lgkmcnt(10)
	s_waitcnt lgkmcnt(9)
	s_waitcnt lgkmcnt(8)
	v_mfma_f32_32x32x16_bf16 v[48:63], v[132:135], v[92:95], v[48:63]
	s_waitcnt lgkmcnt(0)
	v_mfma_f32_32x32x16_bf16 v[64:79], v[88:91], v[96:99], v[64:79]
	ds_read_b64_tr_b16 v[88:89], v179 offset:0x400
	ds_read_b64_tr_b16 v[90:91], v179 offset:0xc00
	ds_read_b64_tr_b16 v[92:93], v179 offset:0x1400
	ds_read_b64_tr_b16 v[94:95], v179 offset:0x1c00
	ds_read_b64_tr_b16 v[96:97], v151 offset:0x400
	ds_read_b64_tr_b16 v[98:99], v151 offset:0xc00
	v_mfma_f32_32x32x16_bf16 v[32:47], v[128:131], v[144:147], v[32:47]
	v_mfma_f32_32x32x16_bf16 v[64:79], v[120:123], v[104:107], v[64:79]
	ds_read_b64_tr_b16 v[104:105], v151 offset:0x1400
	ds_read_b64_tr_b16 v[106:107], v151 offset:0x1c00
	s_nop 0
	s_waitcnt lgkmcnt(0)
	s_nop 0
	v_mfma_f32_32x32x16_bf16 v[16:31], v[128:131], v[88:91], v[16:31]
	ds_read_b64_tr_b16 v[88:89], v179 offset:0x600
	ds_read_b64_tr_b16 v[90:91], v179 offset:0xe00
	v_mfma_f32_32x32x16_bf16 v[32:47], v[132:135], v[152:155], v[32:47]
	v_mfma_f32_32x32x16_bf16 v[16:31], v[132:135], v[92:95], v[16:31]
	ds_read_b64_tr_b16 v[92:93], v179 offset:0x1600
	ds_read_b64_tr_b16 v[94:95], v179 offset:0x1e00
	v_mfma_f32_32x32x16_bf16 v[32:47], v[84:87], v[156:159], v[32:47]
	v_mfma_f32_32x32x16_bf16 v[16:31], v[84:87], v[96:99], v[16:31]
	ds_read_b64_tr_b16 v[96:97], v151 offset:0x600
	ds_read_b64_tr_b16 v[98:99], v151 offset:0xe00
	v_mfma_f32_32x32x16_bf16 v[32:47], v[80:83], v[100:103], v[32:47]
	ds_read_b64_tr_b16 v[100:101], v151 offset:0x1600
	ds_read_b64_tr_b16 v[102:103], v151 offset:0x1e00
	s_nop 0
	s_waitcnt lgkmcnt(0)
	s_nop 0
	v_mfma_f32_32x32x16_bf16 v[0:15], v[128:131], v[88:91], v[0:15]
	v_mfma_f32_32x32x16_bf16 v[64:79], v[112:115], v[108:111], v[64:79]
	v_mfma_f32_32x32x16_bf16 v[0:15], v[132:135], v[92:95], v[0:15]
	v_mfma_f32_32x32x16_bf16 v[64:79], v[124:127], v[116:119], v[64:79]
	v_mfma_f32_32x32x16_bf16 v[0:15], v[84:87], v[96:99], v[0:15]
	s_nop 10
	v_exp_f32_e32 v108, v68
	v_exp_f32_e32 v109, v69
	v_exp_f32_e32 v110, v70
	v_exp_f32_e32 v111, v71
	v_exp_f32_e32 v112, v72
	v_exp_f32_e32 v113, v73
	v_exp_f32_e32 v114, v74
	v_mfma_f32_32x32x16_bf16 v[16:31], v[80:83], v[104:107], v[16:31]
	v_exp_f32_e32 v104, v64
	v_exp_f32_e32 v105, v65
	v_exp_f32_e32 v106, v66
	v_exp_f32_e32 v107, v67
	v_exp_f32_e32 v115, v75
	v_cvt_pk_bf16_f32 v64, v104, v105
	v_cvt_pk_bf16_f32 v66, v108, v109
	v_mfma_f32_32x32x16_bf16 v[48:63], v[84:87], v[136:139], v[48:63]
	v_cvt_pk_bf16_f32 v65, v106, v107
	v_cvt_pk_bf16_f32 v67, v110, v111
	v_cvt_pk_bf16_f32 v68, v112, v113
	v_cvt_pk_bf16_f32 v69, v114, v115
	v_mfma_f32_32x32x16_bf16 v[0:15], v[80:83], v[100:103], v[0:15]
	v_exp_f32_e32 v100, v76
	v_exp_f32_e32 v101, v77
	v_exp_f32_e32 v102, v78
	v_exp_f32_e32 v103, v79
	v_cvt_pk_bf16_f32 v70, v100, v101
	v_cvt_pk_bf16_f32 v71, v102, v103
	ds_write_b128 v181, v[64:67]
	ds_write_b128 v181, v[68:71] offset:1024
	s_waitcnt vmcnt(0) lgkmcnt(0)
	s_barrier
; __device__ __forceinline__ int crow(int r, int hi) { return (r & 3) + 8 * (r >> 2) + 4 * hi; }
; #define WBAR(n) do { asm volatile("s_waitcnt vmcnt(" #n ") lgkmcnt(0)" ::: "memory"); __builtin_amdgcn_s_barrier(); asm volatile("" ::: "memory"); } while (0)
; #define TRB(T, D0, vo_, vt_) do { T[0] = tr_read<v_rd_off(D0, 0, 0)>(vo_); T[1] = tr_read<v_rd_off(D0, 0, 1)>(vo_); T[2] = tr_read<v_rd_off(D0, 1, 0)>(vo_); T[3] = tr_read<v_rd_off(D0, 1, 1)>(vo_); \
;     T[4] = tr_read<v_rd_off(D0, 0, 0)>(vt_); T[5] = tr_read<v_rd_off(D0, 0, 1)>(vt_); T[6] = tr_read<v_rd_off(D0, 1, 0)>(vt_); T[7] = tr_read<v_rd_off(D0, 1, 1)>(vt_); } while (0)
; #define TRW(T, n) asm volatile("s_waitcnt lgkmcnt(" #n ")" : "+v"(T[0]), "+v"(T[1]), "+v"(T[2]), "+v"(T[3]), "+v"(T[4]), "+v"(T[5]), "+v"(T[6]), "+v"(T[7]) :: "memory")
; #define MB(od, T, o0, o1, t0, t1) do { od = __builtin_amdgcn_mfma_f32_32x32x16_bf16(o0, PKV(T[0], T[1]), od, 0, 0, 0); od = __builtin_amdgcn_mfma_f32_32x32x16_bf16(o1, PKV(T[2], T[3]), od, 0, 0, 0); \
;     od = __builtin_amdgcn_mfma_f32_32x32x16_bf16(t0, PKV(T[4], T[5]), od, 0, 0, 0); od = __builtin_amdgcn_mfma_f32_32x32x16_bf16(t1, PKV(T[6], T[7]), od, 0, 0, 0); } while (0)
; #define WBAR(n) do { asm volatile("s_waitcnt vmcnt(" #n ") lgkmcnt(0)" ::: "memory"); __builtin_amdgcn_s_barrier(); asm volatile("" ::: "memory"); } while (0)
; template <int LD> ...
;     ...
;   { const int vo_ = vbo + v1, vt_ = vbt + v1;
;     ot0 = lds_rd128<16384>(pxra); ot1 = lds_rd128<16384 + 1024>(pxra);
;     TRB(trA, 0, vo_, vt_);
;     asm volatile("s_waitcnt lgkmcnt(0)" : "+v"(ot0), "+v"(ot1) :: "memory"); TRW(trA, 0); TRB(trB, 1, vo_, vt_);
;     MB(o[0], trA, ownB0, ownB1, ot0, ot1); TRW(trB, 0); TRB(trA, 2, vo_, vt_);
;     MB(o[1], trB, ownB0, ownB1, ot0, ot1); TRW(trA, 0); TRB(trB, 3, vo_, vt_);
;     MB(o[2], trA, ownB0, ownB1, ot0, ot1); TRW(trB, 0);
;     MB(o[3], trB, ownB0, ownB1, ot0, ot1); }
;   WBAR(0);
;     ...
;   { auto rr = __builtin_amdgcn_permlane32_swap(__float_as_uint(lsum), __float_as_uint(lsum), false, false);
;     lsum = __uint_as_float(rr[0]) + __uint_as_float(rr[1]); }
;   if (hi == 0) xl[wv * 32 + r32] = lsum;
;   __syncthreads();
;   float rli[16];
; #pragma unroll
;   for (int r = 0; r < 16; ++r) { const int cr = crow(r, hi); rli[r] = __builtin_amdgcn_rcpf(xl[wv * 32 + cr] + xl[(wv ^ 1) * 32 + cr]); }
	ds_read_b128 v[72:75], v171 offset:0x4000
	ds_read_b128 v[76:79], v171 offset:0x4400
	v_mfma_f32_32x32x16_bf16 v[48:63], v[80:83], v[140:143], v[48:63]
	ds_read_b64_tr_b16 v[80:81], v177 offset:0
	ds_read_b64_tr_b16 v[82:83], v177 offset:0x800
	ds_read_b64_tr_b16 v[84:85], v177 offset:0x1000
	ds_read_b64_tr_b16 v[86:87], v177 offset:0x1800
	ds_read_b64_tr_b16 v[88:89], v160 offset:0
	ds_read_b64_tr_b16 v[90:91], v160 offset:0x800
	ds_read_b64_tr_b16 v[92:93], v160 offset:0x1000
	ds_read_b64_tr_b16 v[94:95], v160 offset:0x1800
	s_waitcnt lgkmcnt(0)
	s_nop 0
	s_waitcnt lgkmcnt(0)
	s_nop 0
	v_mfma_f32_32x32x16_bf16 v[48:63], v[64:67], v[80:83], v[48:63]
	ds_read_b64_tr_b16 v[80:81], v177 offset:0x200
	ds_read_b64_tr_b16 v[82:83], v177 offset:0xa00
	v_mfma_f32_32x32x16_bf16 v[48:63], v[68:71], v[84:87], v[48:63]
	ds_read_b64_tr_b16 v[84:85], v177 offset:0x1200
	ds_read_b64_tr_b16 v[86:87], v177 offset:0x1a00
	v_mfma_f32_32x32x16_bf16 v[48:63], v[72:75], v[88:91], v[48:63]
	ds_read_b64_tr_b16 v[88:89], v160 offset:0x200
	ds_read_b64_tr_b16 v[90:91], v160 offset:0xa00
	ds_read_b64_tr_b16 v[96:97], v160 offset:0x1200
	ds_read_b64_tr_b16 v[98:99], v160 offset:0x1a00
	s_nop 0
	s_waitcnt lgkmcnt(0)
	s_nop 0
	v_mfma_f32_32x32x16_bf16 v[32:47], v[64:67], v[80:83], v[32:47]
	ds_read_b64_tr_b16 v[80:81], v177 offset:0x400
	ds_read_b64_tr_b16 v[82:83], v177 offset:0xc00
	v_mfma_f32_32x32x16_bf16 v[32:47], v[68:71], v[84:87], v[32:47]
	ds_read_b64_tr_b16 v[84:85], v177 offset:0x1400
	ds_read_b64_tr_b16 v[86:87], v177 offset:0x1c00
	v_mfma_f32_32x32x16_bf16 v[32:47], v[72:75], v[88:91], v[32:47]
	ds_read_b64_tr_b16 v[88:89], v160 offset:0x400
	ds_read_b64_tr_b16 v[90:91], v160 offset:0xc00
	v_mfma_f32_32x32x16_bf16 v[48:63], v[76:79], v[92:95], v[48:63]
	ds_read_b64_tr_b16 v[92:93], v160 offset:0x1400
	ds_read_b64_tr_b16 v[94:95], v160 offset:0x1c00
	s_nop 0
	s_waitcnt lgkmcnt(0)
	s_nop 0
	v_mfma_f32_32x32x16_bf16 v[16:31], v[64:67], v[80:83], v[16:31]
	v_add_f32_e32 v80, v170, v104
	v_add_f32_e32 v104, v105, v80
	ds_read_b64_tr_b16 v[80:81], v177 offset:0x600
	ds_read_b64_tr_b16 v[82:83], v177 offset:0xe00
	v_mfma_f32_32x32x16_bf16 v[16:31], v[68:71], v[84:87], v[16:31]
	ds_read_b64_tr_b16 v[84:85], v177 offset:0x1600
	ds_read_b64_tr_b16 v[86:87], v177 offset:0x1e00
	v_mfma_f32_32x32x16_bf16 v[16:31], v[72:75], v[88:91], v[16:31]
	ds_read_b64_tr_b16 v[88:89], v160 offset:0x600
	ds_read_b64_tr_b16 v[90:91], v160 offset:0xe00
	v_mfma_f32_32x32x16_bf16 v[32:47], v[76:79], v[96:99], v[32:47]
	ds_read_b64_tr_b16 v[96:97], v160 offset:0x1600
	ds_read_b64_tr_b16 v[98:99], v160 offset:0x1e00
	s_nop 0
	s_waitcnt lgkmcnt(0)
	s_waitcnt vmcnt(0) lgkmcnt(0)
	s_barrier
	v_mfma_f32_32x32x16_bf16 v[0:15], v[64:67], v[80:83], v[0:15]
	v_add_f32_e32 v64, v106, v104
	v_add_f32_e32 v64, v107, v64
	v_add_f32_e32 v64, v108, v64
	v_add_f32_e32 v64, v109, v64
	v_add_f32_e32 v64, v110, v64
	v_add_f32_e32 v64, v111, v64
	v_add_f32_e32 v64, v112, v64
	v_mfma_f32_32x32x16_bf16 v[0:15], v[68:71], v[84:87], v[0:15]
	v_add_f32_e32 v64, v113, v64
	v_add_f32_e32 v64, v114, v64
	v_add_f32_e32 v64, v115, v64
	v_add_f32_e32 v64, v100, v64
	v_add_f32_e32 v64, v101, v64
	v_add_f32_e32 v64, v102, v64
	v_add_f32_e32 v64, v103, v64
	v_mfma_f32_32x32x16_bf16 v[0:15], v[72:75], v[88:91], v[0:15]
	v_mov_b32_e32 v65, v64
	s_nop 1
	v_permlane32_swap_b32_e32 v64, v65
	v_mfma_f32_32x32x16_bf16 v[16:31], v[76:79], v[92:95], v[16:31]
	v_mfma_f32_32x32x16_bf16 v[0:15], v[76:79], v[96:99], v[0:15]
	s_and_saveexec_b64 s[52:53], vcc
	v_lshl_add_u32 v66, v150, 2, s38
	v_add_f32_e32 v64, v64, v65
	ds_write_b32 v66, v64
	s_or_b64 exec, exec, s[52:53]
	v_add_u32_e32 v92, s38, v178
	v_add_u32_e32 v93, s39, v178
	s_waitcnt vmcnt(0) lgkmcnt(0)
	s_barrier
	ds_read_b128 v[64:67], v92
	ds_read_b128 v[68:71], v92 offset:32
	ds_read_b128 v[72:75], v93
	ds_read_b128 v[76:79], v93 offset:32
	v_ashrrev_i32_e32 v151, 31, v150
	v_lshl_add_u64 v[96:97], v[150:151], 4, s[8:9]
	s_mov_b64 s[52:53], -1
	s_waitcnt lgkmcnt(1)
	v_add_f32_e32 v64, v64, v72
	v_rcp_f32_e32 v80, v64
	v_add_f32_e32 v64, v65, v73
	v_rcp_f32_e32 v81, v64
	v_add_f32_e32 v64, v66, v74
	v_rcp_f32_e32 v82, v64
	v_add_f32_e32 v64, v67, v75
	v_rcp_f32_e32 v83, v64
	s_waitcnt lgkmcnt(0)
	v_add_f32_e32 v64, v68, v76
	v_rcp_f32_e32 v84, v64
	v_add_f32_e32 v64, v69, v77
	v_rcp_f32_e32 v85, v64
	v_add_f32_e32 v64, v70, v78
	v_rcp_f32_e32 v86, v64
	v_add_f32_e32 v64, v71, v79
	v_rcp_f32_e32 v87, v64
	ds_read_b128 v[64:67], v92 offset:64
	ds_read_b128 v[68:71], v93 offset:64
	s_and_b64 vcc, exec, s[2:3]
	s_waitcnt lgkmcnt(0)
	v_add_f32_e32 v64, v64, v68
	v_rcp_f32_e32 v88, v64
	v_add_f32_e32 v64, v65, v69
	v_rcp_f32_e32 v89, v64
	v_add_f32_e32 v64, v66, v70
	v_rcp_f32_e32 v90, v64
	v_add_f32_e32 v64, v67, v71
	v_rcp_f32_e32 v91, v64
	ds_read_b128 v[64:67], v92 offset:96
	ds_read_b128 v[68:71], v93 offset:96
	s_waitcnt lgkmcnt(0)
	v_add_f32_e32 v64, v64, v68
	v_rcp_f32_e32 v92, v64
	v_add_f32_e32 v64, v65, v69
	v_rcp_f32_e32 v93, v64
	v_add_f32_e32 v64, v66, v70
	v_rcp_f32_e32 v94, v64
	v_add_f32_e32 v64, v67, v71
	v_rcp_f32_e32 v95, v64
	s_cbranch_vccz .LBB0_29
; template <int LD> ...
;     ...
;   float ss[16];
; #pragma unroll
;   for (int r = 0; r < 16; ++r) ss[r] = 0.f;
; #pragma unroll
;   for (int d0 = 0; d0 < 4; ++d0)
; #pragma unroll
;     for (int q4 = 0; q4 < 2; ++q4) { const u32x4 w = st[(d0 * 2 + q4) * 64];
; #pragma unroll
;       for (int e = 0; e < 4; ++e) { const unsigned u = w[e]; const int q = 4 * q4 + e;
;         const float da = __uint_as_float(u << 16) - epi.lam * (o[d0][2 * q] * rli[2 * q]);
;         const float db = __uint_as_float(u & 0xffff0000u) - epi.lam * (o[d0][2 * q + 1] * rli[2 * q + 1]);
;         o[d0][2 * q] = da; o[d0][2 * q + 1] = db; ss[2 * q] += da * da; ss[2 * q + 1] += db * db; } }
	global_load_dwordx4 v[182:185], v[96:97], off
	global_load_dwordx4 v[186:189], v[96:97], off offset:1024
	global_load_dwordx4 v[190:193], v[96:97], off offset:2048
	global_load_dwordx4 v[194:197], v[96:97], off offset:3072
	v_add_co_u32_e32 v122, vcc, s56, v96
	v_pk_mul_f32 v[120:121], v[50:51], v[82:83]
	s_nop 0
	v_addc_co_u32_e32 v123, vcc, 0, v97, vcc
	global_load_dwordx4 v[198:201], v[122:123], off
	global_load_dwordx4 v[220:223], v[122:123], off offset:1024
	global_load_dwordx4 v[224:227], v[122:123], off offset:2048
	global_load_dwordx4 v[228:231], v[122:123], off offset:3072
	v_pk_mul_f32 v[168:169], v[34:35], v[82:83]
	v_pk_mul_f32 v[140:141], v[54:55], v[86:87]
	v_pk_mul_f32 v[156:157], v[38:39], v[86:87]
	v_pk_mul_f32 v[136:137], v[42:43], v[90:91]
	v_pk_mul_f32 v[116:117], v[58:59], v[90:91]
	v_pk_mul_f32 v[146:147], v[40:41], v[88:89]
	v_pk_mul_f32 v[152:153], v[52:53], v[84:85]
	v_pk_mul_f32 v[172:173], v[36:37], v[84:85]
	v_pk_mul_f32 v[100:101], v[62:63], v[94:95]
	v_pk_mul_f32 v[112:113], v[46:47], v[94:95]
	v_pk_mul_f32 v[104:105], v[60:61], v[92:93]
	v_pk_mul_f32 v[114:115], v[32:33], v[80:81]
	v_pk_mul_f32 v[128:129], v[44:45], v[92:93]
	v_pk_mul_f32 v[106:107], v[48:49], v[80:81]
	v_pk_mul_f32 v[130:131], v[56:57], v[88:89]
	v_cmp_eq_u32_e32 vcc, 0, v215
	s_waitcnt vmcnt(7)
	v_lshlrev_b32_e32 v64, 16, v182
	v_and_b32_e32 v65, 0xffff0000, v182
	v_lshlrev_b32_e32 v118, 16, v183
	v_and_b32_e32 v119, 0xffff0000, v183
	v_lshlrev_b32_e32 v150, 16, v184
	v_and_b32_e32 v151, 0xffff0000, v184
	v_lshlrev_b32_e32 v138, 16, v185
	v_and_b32_e32 v139, 0xffff0000, v185
	v_pk_fma_f32 v[118:119], v[148:149], v[120:121], v[118:119] neg_lo:[1,0,0] neg_hi:[1,0,0]
	v_pk_fma_f32 v[138:139], v[148:149], v[140:141], v[138:139] neg_lo:[1,0,0] neg_hi:[1,0,0]
	v_pk_fma_f32 v[150:151], v[148:149], v[152:153], v[150:151] neg_lo:[1,0,0] neg_hi:[1,0,0]
	v_pk_fma_f32 v[106:107], v[148:149], v[106:107], v[64:65] neg_lo:[1,0,0] neg_hi:[1,0,0]
	s_waitcnt vmcnt(6)
	v_lshlrev_b32_e32 v76, 16, v186
	v_and_b32_e32 v77, 0xffff0000, v186
	v_lshlrev_b32_e32 v78, 16, v187
	v_and_b32_e32 v79, 0xffff0000, v187
	v_lshlrev_b32_e32 v102, 16, v188
	v_and_b32_e32 v103, 0xffff0000, v188
	v_lshlrev_b32_e32 v98, 16, v189
	v_and_b32_e32 v99, 0xffff0000, v189
	v_pk_fma_f32 v[116:117], v[148:149], v[116:117], v[78:79] neg_lo:[1,0,0] neg_hi:[1,0,0]
	v_pk_fma_f32 v[98:99], v[148:149], v[100:101], v[98:99] neg_lo:[1,0,0] neg_hi:[1,0,0]
	v_pk_fma_f32 v[102:103], v[148:149], v[104:105], v[102:103] neg_lo:[1,0,0] neg_hi:[1,0,0]
	v_pk_fma_f32 v[130:131], v[148:149], v[130:131], v[76:77] neg_lo:[1,0,0] neg_hi:[1,0,0]
	s_waitcnt vmcnt(5)
	v_lshlrev_b32_e32 v108, 16, v190
	v_and_b32_e32 v109, 0xffff0000, v190
	v_lshlrev_b32_e32 v166, 16, v191
	v_and_b32_e32 v167, 0xffff0000, v191
	v_lshlrev_b32_e32 v170, 16, v192
	v_and_b32_e32 v171, 0xffff0000, v192
	v_lshlrev_b32_e32 v154, 16, v193
	v_and_b32_e32 v155, 0xffff0000, v193
	v_pk_fma_f32 v[120:121], v[148:149], v[168:169], v[166:167] neg_lo:[1,0,0] neg_hi:[1,0,0]
	v_pk_fma_f32 v[140:141], v[148:149], v[156:157], v[154:155] neg_lo:[1,0,0] neg_hi:[1,0,0]
	v_pk_mul_f32 v[166:167], v[120:121], v[120:121]
	v_pk_mul_f32 v[154:155], v[140:141], v[140:141]
	v_pk_fma_f32 v[168:169], v[118:119], v[118:119], v[166:167]
	v_pk_mul_f32 v[166:167], v[18:19], v[82:83]
	v_pk_fma_f32 v[156:157], v[138:139], v[138:139], v[154:155]
	v_pk_mul_f32 v[154:155], v[22:23], v[86:87]
	v_pk_fma_f32 v[152:153], v[148:149], v[172:173], v[170:171] neg_lo:[1,0,0] neg_hi:[1,0,0]
	v_pk_fma_f32 v[108:109], v[148:149], v[114:115], v[108:109] neg_lo:[1,0,0] neg_hi:[1,0,0]
	v_pk_mul_f32 v[114:115], v[16:17], v[80:81]
	v_pk_mul_f32 v[64:65], v[108:109], v[108:109]
	v_pk_mul_f32 v[170:171], v[20:21], v[84:85]
	v_pk_fma_f32 v[64:65], v[106:107], v[106:107], v[64:65]
	s_waitcnt vmcnt(4)
	v_lshlrev_b32_e32 v144, 16, v194
	v_and_b32_e32 v145, 0xffff0000, v194
	v_lshlrev_b32_e32 v134, 16, v195
	v_and_b32_e32 v135, 0xffff0000, v195
	v_lshlrev_b32_e32 v126, 16, v196
	v_and_b32_e32 v127, 0xffff0000, v196
	v_lshlrev_b32_e32 v110, 16, v197
	v_and_b32_e32 v111, 0xffff0000, v197
	v_pk_fma_f32 v[134:135], v[148:149], v[136:137], v[134:135] neg_lo:[1,0,0] neg_hi:[1,0,0]
	v_pk_fma_f32 v[144:145], v[148:149], v[146:147], v[144:145] neg_lo:[1,0,0] neg_hi:[1,0,0]
	v_pk_mul_f32 v[146:147], v[24:25], v[88:89]
	v_pk_mul_f32 v[78:79], v[134:135], v[134:135]
	v_pk_mul_f32 v[136:137], v[26:27], v[90:91]
	v_pk_fma_f32 v[78:79], v[116:117], v[116:117], v[78:79]
	v_pk_fma_f32 v[100:101], v[148:149], v[112:113], v[110:111] neg_lo:[1,0,0] neg_hi:[1,0,0]
	v_pk_fma_f32 v[104:105], v[148:149], v[128:129], v[126:127] neg_lo:[1,0,0] neg_hi:[1,0,0]
	v_pk_mul_f32 v[110:111], v[100:101], v[100:101]
	v_pk_mul_f32 v[76:77], v[144:145], v[144:145]
	v_pk_fma_f32 v[112:113], v[98:99], v[98:99], v[110:111]
	v_pk_mul_f32 v[110:111], v[30:31], v[94:95]
	v_pk_mul_f32 v[126:127], v[28:29], v[92:93]
	v_pk_fma_f32 v[76:77], v[130:131], v[130:131], v[76:77]
	s_waitcnt vmcnt(3)
	v_lshlrev_b32_e32 v176, 16, v200
	v_and_b32_e32 v177, 0xffff0000, v200
	v_lshlrev_b32_e32 v174, 16, v201
	v_and_b32_e32 v175, 0xffff0000, v201
	v_lshlrev_b32_e32 v180, 16, v198
	v_and_b32_e32 v181, 0xffff0000, v198
	v_lshlrev_b32_e32 v66, 16, v199
	v_and_b32_e32 v67, 0xffff0000, v199
	v_pk_fma_f32 v[166:167], v[148:149], v[166:167], v[66:67] neg_lo:[1,0,0] neg_hi:[1,0,0]
	v_pk_fma_f32 v[154:155], v[148:149], v[154:155], v[174:175] neg_lo:[1,0,0] neg_hi:[1,0,0]
	v_pk_fma_f32 v[66:67], v[166:167], v[166:167], v[168:169]
	v_pk_mul_f32 v[168:169], v[2:3], v[82:83]
	v_pk_fma_f32 v[174:175], v[154:155], v[154:155], v[156:157]
	v_pk_mul_f32 v[156:157], v[6:7], v[86:87]
	v_pk_fma_f32 v[114:115], v[148:149], v[114:115], v[180:181] neg_lo:[1,0,0] neg_hi:[1,0,0]
	v_pk_mul_f32 v[180:181], v[0:1], v[80:81]
	v_pk_fma_f32 v[170:171], v[148:149], v[170:171], v[176:177] neg_lo:[1,0,0] neg_hi:[1,0,0]
	v_pk_mul_f32 v[176:177], v[4:5], v[84:85]
	v_pk_fma_f32 v[64:65], v[114:115], v[114:115], v[64:65]
	s_waitcnt vmcnt(2)
; template <int X> __device__ __forceinline__ float swz_xor(float v) { return __int_as_float(__builtin_amdgcn_ds_swizzle(__float_as_int(v), (X << 10) | 0x1f)); }
; template <int LD> ...
;     ...
;   for (int d0 = 0; d0 < 4; ++d0)
; #pragma unroll
;     for (int q4 = 0; q4 < 2; ++q4) { const u32x4 w = st[(d0 * 2 + q4) * 64];
; #pragma unroll
;       for (int e = 0; e < 4; ++e) { const unsigned u = w[e]; const int q = 4 * q4 + e;
;         const float da = __uint_as_float(u << 16) - epi.lam * (o[d0][2 * q] * rli[2 * q]);
;         const float db = __uint_as_float(u & 0xffff0000u) - epi.lam * (o[d0][2 * q + 1] * rli[2 * q + 1]);
;         o[d0][2 * q] = da; o[d0][2 * q + 1] = db; ss[2 * q] += da * da; ss[2 * q + 1] += db * db; } }
; #pragma unroll
;   for (int r = 0; r < 16; ++r) { ss[r] += swz_xor<1>(ss[r]); ss[r] += swz_xor<2>(ss[r]); ss[r] += swz_xor<4>(ss[r]); ss[r] += swz_xor<8>(ss[r]); ss[r] += swz_xor<16>(ss[r]); }
	v_lshlrev_b32_e32 v158, 16, v220
	v_and_b32_e32 v159, 0xffff0000, v220
	v_lshlrev_b32_e32 v142, 16, v221
	v_and_b32_e32 v143, 0xffff0000, v221
	v_lshlrev_b32_e32 v132, 16, v222
	v_and_b32_e32 v133, 0xffff0000, v222
	v_lshlrev_b32_e32 v124, 16, v223
	v_and_b32_e32 v125, 0xffff0000, v223
	v_pk_fma_f32 v[146:147], v[148:149], v[146:147], v[158:159] neg_lo:[1,0,0] neg_hi:[1,0,0]
	v_pk_fma_f32 v[136:137], v[148:149], v[136:137], v[142:143] neg_lo:[1,0,0] neg_hi:[1,0,0]
	v_pk_mul_f32 v[142:143], v[10:11], v[90:91]
	v_pk_fma_f32 v[78:79], v[136:137], v[136:137], v[78:79]
	v_pk_fma_f32 v[110:111], v[148:149], v[110:111], v[124:125] neg_lo:[1,0,0] neg_hi:[1,0,0]
	v_pk_fma_f32 v[126:127], v[148:149], v[126:127], v[132:133] neg_lo:[1,0,0] neg_hi:[1,0,0]
	v_pk_mul_f32 v[132:133], v[12:13], v[92:93]
	v_pk_fma_f32 v[124:125], v[110:111], v[110:111], v[112:113]
	v_pk_mul_f32 v[112:113], v[14:15], v[94:95]
	v_pk_fma_f32 v[76:77], v[146:147], v[146:147], v[76:77]
	s_waitcnt vmcnt(1)
	v_lshlrev_b32_e32 v122, 16, v224
	v_and_b32_e32 v123, 0xffff0000, v224
	v_lshlrev_b32_e32 v72, 16, v225
	v_and_b32_e32 v73, 0xffff0000, v225
	s_waitcnt vmcnt(0)
	v_lshlrev_b32_e32 v158, 16, v228
	v_and_b32_e32 v159, 0xffff0000, v228
	v_lshlrev_b32_e32 v68, 16, v229
	v_and_b32_e32 v69, 0xffff0000, v229
	v_pk_fma_f32 v[168:169], v[148:149], v[168:169], v[72:73] neg_lo:[1,0,0] neg_hi:[1,0,0]
	v_lshlrev_b32_e32 v172, 16, v226
	v_and_b32_e32 v173, 0xffff0000, v226
	v_lshlrev_b32_e32 v74, 16, v227
	v_and_b32_e32 v75, 0xffff0000, v227
	v_pk_fma_f32 v[142:143], v[148:149], v[142:143], v[68:69] neg_lo:[1,0,0] neg_hi:[1,0,0]
	v_pk_fma_f32 v[66:67], v[168:169], v[168:169], v[66:67]
	v_pk_fma_f32 v[156:157], v[148:149], v[156:157], v[74:75] neg_lo:[1,0,0] neg_hi:[1,0,0]
	v_pk_fma_f32 v[68:69], v[142:143], v[142:143], v[78:79]
	ds_swizzle_b32 v72, v66 offset:swizzle(SWAP,1)
	ds_swizzle_b32 v73, v67 offset:swizzle(SWAP,1)
	v_pk_fma_f32 v[74:75], v[156:157], v[156:157], v[174:175]
	ds_swizzle_b32 v78, v68 offset:swizzle(SWAP,1)
	ds_swizzle_b32 v79, v69 offset:swizzle(SWAP,1)
	ds_swizzle_b32 v174, v74 offset:swizzle(SWAP,1)
	ds_swizzle_b32 v175, v75 offset:swizzle(SWAP,1)
	s_waitcnt lgkmcnt(4)
	v_pk_add_f32 v[66:67], v[66:67], v[72:73]
	ds_swizzle_b32 v72, v66 offset:swizzle(SWAP,2)
	s_waitcnt lgkmcnt(3)
	v_pk_add_f32 v[68:69], v[68:69], v[78:79]
	ds_swizzle_b32 v73, v67 offset:swizzle(SWAP,2)
	s_waitcnt lgkmcnt(2)
	v_pk_add_f32 v[74:75], v[74:75], v[174:175]
	ds_swizzle_b32 v78, v68 offset:swizzle(SWAP,2)
	ds_swizzle_b32 v79, v69 offset:swizzle(SWAP,2)
	ds_swizzle_b32 v174, v74 offset:swizzle(SWAP,2)
	ds_swizzle_b32 v175, v75 offset:swizzle(SWAP,2)
	s_waitcnt lgkmcnt(4)
	v_pk_add_f32 v[66:67], v[66:67], v[72:73]
	ds_swizzle_b32 v72, v66 offset:swizzle(SWAP,4)
	s_waitcnt lgkmcnt(3)
	v_pk_add_f32 v[68:69], v[68:69], v[78:79]
	ds_swizzle_b32 v73, v67 offset:swizzle(SWAP,4)
	s_waitcnt lgkmcnt(2)
	v_pk_add_f32 v[74:75], v[74:75], v[174:175]
	ds_swizzle_b32 v78, v68 offset:swizzle(SWAP,4)
	ds_swizzle_b32 v79, v69 offset:swizzle(SWAP,4)
	ds_swizzle_b32 v174, v74 offset:swizzle(SWAP,4)
	ds_swizzle_b32 v175, v75 offset:swizzle(SWAP,4)
	s_waitcnt lgkmcnt(4)
	v_pk_add_f32 v[66:67], v[66:67], v[72:73]
	ds_swizzle_b32 v72, v66 offset:swizzle(SWAP,8)
	s_waitcnt lgkmcnt(3)
	v_pk_add_f32 v[68:69], v[68:69], v[78:79]
	ds_swizzle_b32 v73, v67 offset:swizzle(SWAP,8)
	s_waitcnt lgkmcnt(2)
	v_pk_add_f32 v[74:75], v[74:75], v[174:175]
	ds_swizzle_b32 v78, v68 offset:swizzle(SWAP,8)
	ds_swizzle_b32 v79, v69 offset:swizzle(SWAP,8)
	ds_swizzle_b32 v174, v74 offset:swizzle(SWAP,8)
	ds_swizzle_b32 v175, v75 offset:swizzle(SWAP,8)
	s_waitcnt lgkmcnt(4)
	v_pk_add_f32 v[66:67], v[66:67], v[72:73]
	ds_swizzle_b32 v72, v66 offset:swizzle(SWAP,16)
	s_waitcnt lgkmcnt(3)
	v_pk_add_f32 v[68:69], v[68:69], v[78:79]
	ds_swizzle_b32 v73, v67 offset:swizzle(SWAP,16)
	s_waitcnt lgkmcnt(2)
	v_pk_add_f32 v[74:75], v[74:75], v[174:175]
	ds_swizzle_b32 v78, v68 offset:swizzle(SWAP,16)
	ds_swizzle_b32 v79, v69 offset:swizzle(SWAP,16)
	ds_swizzle_b32 v174, v74 offset:swizzle(SWAP,16)
	ds_swizzle_b32 v175, v75 offset:swizzle(SWAP,16)
	s_waitcnt lgkmcnt(4)
	v_pk_add_f32 v[66:67], v[66:67], v[72:73]
	v_pk_mul_f32 v[72:73], v[152:153], v[152:153]
	s_waitcnt lgkmcnt(2)
	v_pk_add_f32 v[78:79], v[68:69], v[78:79]
	v_pk_mul_f32 v[68:69], v[104:105], v[104:105]
	v_pk_fma_f32 v[72:73], v[150:151], v[150:151], v[72:73]
	s_waitcnt lgkmcnt(0)
	v_pk_add_f32 v[74:75], v[74:75], v[174:175]
	v_pk_mul_f32 v[174:175], v[8:9], v[88:89]
	v_pk_fma_f32 v[68:69], v[102:103], v[102:103], v[68:69]
	v_lshlrev_b32_e32 v128, 16, v230
	v_and_b32_e32 v129, 0xffff0000, v230
	v_lshlrev_b32_e32 v70, 16, v231
	v_and_b32_e32 v71, 0xffff0000, v231
	v_pk_fma_f32 v[122:123], v[148:149], v[180:181], v[122:123] neg_lo:[1,0,0] neg_hi:[1,0,0]
	v_pk_fma_f32 v[72:73], v[170:171], v[170:171], v[72:73]
	v_pk_fma_f32 v[172:173], v[148:149], v[176:177], v[172:173] neg_lo:[1,0,0] neg_hi:[1,0,0]
	v_pk_fma_f32 v[158:159], v[148:149], v[174:175], v[158:159] neg_lo:[1,0,0] neg_hi:[1,0,0]
	v_pk_fma_f32 v[68:69], v[126:127], v[126:127], v[68:69]
	v_pk_fma_f32 v[128:129], v[148:149], v[132:133], v[128:129] neg_lo:[1,0,0] neg_hi:[1,0,0]
	v_pk_fma_f32 v[112:113], v[148:149], v[112:113], v[70:71] neg_lo:[1,0,0] neg_hi:[1,0,0]
	v_pk_fma_f32 v[64:65], v[122:123], v[122:123], v[64:65]
	v_pk_fma_f32 v[72:73], v[172:173], v[172:173], v[72:73]
	v_pk_fma_f32 v[76:77], v[158:159], v[158:159], v[76:77]
	v_pk_fma_f32 v[68:69], v[128:129], v[128:129], v[68:69]
	v_pk_fma_f32 v[70:71], v[112:113], v[112:113], v[124:125]
	ds_swizzle_b32 v180, v64 offset:swizzle(SWAP,1)
	ds_swizzle_b32 v181, v65 offset:swizzle(SWAP,1)
	ds_swizzle_b32 v176, v72 offset:swizzle(SWAP,1)
	ds_swizzle_b32 v177, v73 offset:swizzle(SWAP,1)
	ds_swizzle_b32 v174, v76 offset:swizzle(SWAP,1)
	ds_swizzle_b32 v175, v77 offset:swizzle(SWAP,1)
	ds_swizzle_b32 v132, v68 offset:swizzle(SWAP,1)
	ds_swizzle_b32 v133, v69 offset:swizzle(SWAP,1)
	ds_swizzle_b32 v124, v70 offset:swizzle(SWAP,1)
	ds_swizzle_b32 v125, v71 offset:swizzle(SWAP,1)
	s_waitcnt lgkmcnt(8)
; template <int X> __device__ __forceinline__ float swz_xor(float v) { return __int_as_float(__builtin_amdgcn_ds_swizzle(__float_as_int(v), (X << 10) | 0x1f)); }
; __device__ __forceinline__ int crow(int r, int hi) { return (r & 3) + 8 * (r >> 2) + 4 * hi; }
; template <int LD> ...
;     ...
;   for (int r = 0; r < 16; ++r) { ss[r] += swz_xor<1>(ss[r]); ss[r] += swz_xor<2>(ss[r]); ss[r] += swz_xor<4>(ss[r]); ss[r] += swz_xor<8>(ss[r]); ss[r] += swz_xor<16>(ss[r]); }
;   if (r32 == 0) {
; #pragma unroll
;     for (int r = 0; r < 16; ++r) xs[wv * 32 + crow(r, hi)] = ss[r]; }
;   __syncthreads();
;   float* stg = (float*)(lds + wv * 16384);
;   unsigned wb = (unsigned)(4 * hi * 128 + r32); asm volatile("" : "+v"(wb));
; #pragma unroll
;   for (int r = 0; r < 16; ++r) { const unsigned cr = (r & 3) + 8 * (r >> 2);
;     const float rs = __builtin_amdgcn_rsqf((ss[r] + xs[(wv ^ 1) * 32 + cr + 4 * hi]) * (1.f / 256.f) + EPS) * epi.oscale;
; #pragma unroll
;     for (int d0 = 0; d0 < 4; ++d0) stg[wb + cr * 128 + d0 * 32] = o[d0][r] * rs; }
	v_pk_add_f32 v[64:65], v[64:65], v[180:181]
	s_waitcnt lgkmcnt(6)
	v_pk_add_f32 v[72:73], v[72:73], v[176:177]
	s_waitcnt lgkmcnt(4)
	v_pk_add_f32 v[76:77], v[76:77], v[174:175]
	s_waitcnt lgkmcnt(2)
	v_pk_add_f32 v[68:69], v[68:69], v[132:133]
	s_waitcnt lgkmcnt(0)
	v_pk_add_f32 v[70:71], v[70:71], v[124:125]
	ds_swizzle_b32 v180, v64 offset:swizzle(SWAP,2)
	ds_swizzle_b32 v181, v65 offset:swizzle(SWAP,2)
	ds_swizzle_b32 v176, v72 offset:swizzle(SWAP,2)
	ds_swizzle_b32 v177, v73 offset:swizzle(SWAP,2)
	ds_swizzle_b32 v174, v76 offset:swizzle(SWAP,2)
	ds_swizzle_b32 v175, v77 offset:swizzle(SWAP,2)
	ds_swizzle_b32 v132, v68 offset:swizzle(SWAP,2)
	ds_swizzle_b32 v133, v69 offset:swizzle(SWAP,2)
	ds_swizzle_b32 v124, v70 offset:swizzle(SWAP,2)
	ds_swizzle_b32 v125, v71 offset:swizzle(SWAP,2)
	s_waitcnt lgkmcnt(8)
	v_pk_add_f32 v[64:65], v[64:65], v[180:181]
	s_waitcnt lgkmcnt(6)
	v_pk_add_f32 v[72:73], v[72:73], v[176:177]
	s_waitcnt lgkmcnt(4)
	v_pk_add_f32 v[76:77], v[76:77], v[174:175]
	s_waitcnt lgkmcnt(2)
	v_pk_add_f32 v[68:69], v[68:69], v[132:133]
	s_waitcnt lgkmcnt(0)
	v_pk_add_f32 v[70:71], v[70:71], v[124:125]
	ds_swizzle_b32 v180, v64 offset:swizzle(SWAP,4)
	ds_swizzle_b32 v181, v65 offset:swizzle(SWAP,4)
	ds_swizzle_b32 v176, v72 offset:swizzle(SWAP,4)
	ds_swizzle_b32 v177, v73 offset:swizzle(SWAP,4)
	ds_swizzle_b32 v174, v76 offset:swizzle(SWAP,4)
	ds_swizzle_b32 v175, v77 offset:swizzle(SWAP,4)
	ds_swizzle_b32 v132, v68 offset:swizzle(SWAP,4)
	ds_swizzle_b32 v133, v69 offset:swizzle(SWAP,4)
	ds_swizzle_b32 v124, v70 offset:swizzle(SWAP,4)
	ds_swizzle_b32 v125, v71 offset:swizzle(SWAP,4)
	s_waitcnt lgkmcnt(8)
	v_pk_add_f32 v[64:65], v[64:65], v[180:181]
	s_waitcnt lgkmcnt(6)
	v_pk_add_f32 v[72:73], v[72:73], v[176:177]
	s_waitcnt lgkmcnt(4)
	v_pk_add_f32 v[76:77], v[76:77], v[174:175]
	s_waitcnt lgkmcnt(2)
	v_pk_add_f32 v[68:69], v[68:69], v[132:133]
	s_waitcnt lgkmcnt(0)
	v_pk_add_f32 v[70:71], v[70:71], v[124:125]
	ds_swizzle_b32 v180, v64 offset:swizzle(SWAP,8)
	ds_swizzle_b32 v181, v65 offset:swizzle(SWAP,8)
	ds_swizzle_b32 v176, v72 offset:swizzle(SWAP,8)
	ds_swizzle_b32 v177, v73 offset:swizzle(SWAP,8)
	ds_swizzle_b32 v174, v76 offset:swizzle(SWAP,8)
	ds_swizzle_b32 v175, v77 offset:swizzle(SWAP,8)
	ds_swizzle_b32 v132, v68 offset:swizzle(SWAP,8)
	ds_swizzle_b32 v133, v69 offset:swizzle(SWAP,8)
	ds_swizzle_b32 v124, v70 offset:swizzle(SWAP,8)
	ds_swizzle_b32 v125, v71 offset:swizzle(SWAP,8)
	s_waitcnt lgkmcnt(8)
	v_pk_add_f32 v[64:65], v[64:65], v[180:181]
	s_waitcnt lgkmcnt(6)
	v_pk_add_f32 v[72:73], v[72:73], v[176:177]
	s_waitcnt lgkmcnt(4)
	v_pk_add_f32 v[76:77], v[76:77], v[174:175]
	s_waitcnt lgkmcnt(2)
	v_pk_add_f32 v[68:69], v[68:69], v[132:133]
	s_waitcnt lgkmcnt(0)
	v_pk_add_f32 v[70:71], v[70:71], v[124:125]
	ds_swizzle_b32 v180, v64 offset:swizzle(SWAP,16)
	ds_swizzle_b32 v181, v65 offset:swizzle(SWAP,16)
	ds_swizzle_b32 v176, v72 offset:swizzle(SWAP,16)
	ds_swizzle_b32 v177, v73 offset:swizzle(SWAP,16)
	ds_swizzle_b32 v174, v76 offset:swizzle(SWAP,16)
	ds_swizzle_b32 v175, v77 offset:swizzle(SWAP,16)
	ds_swizzle_b32 v132, v68 offset:swizzle(SWAP,16)
	ds_swizzle_b32 v133, v69 offset:swizzle(SWAP,16)
	ds_swizzle_b32 v124, v70 offset:swizzle(SWAP,16)
	ds_swizzle_b32 v125, v71 offset:swizzle(SWAP,16)
	s_waitcnt lgkmcnt(8)
	v_pk_add_f32 v[64:65], v[64:65], v[180:181]
	s_waitcnt lgkmcnt(6)
	v_pk_add_f32 v[72:73], v[72:73], v[176:177]
	s_waitcnt lgkmcnt(4)
	v_pk_add_f32 v[76:77], v[76:77], v[174:175]
	s_waitcnt lgkmcnt(2)
	v_pk_add_f32 v[68:69], v[68:69], v[132:133]
	s_waitcnt lgkmcnt(0)
	v_pk_add_f32 v[70:71], v[70:71], v[124:125]
	s_and_saveexec_b64 s[52:53], vcc
	s_cbranch_execz .LBB0_28
	v_add_u32_e32 v124, s40, v178
	ds_write_b128 v124, v[64:67]
	ds_write_b128 v124, v[72:75] offset:32
	ds_write_b128 v124, v[76:79] offset:64
	ds_write_b128 v124, v[68:71] offset:96
.LBB0_28:
	s_or_b64 exec, exec, s[52:53]
	v_lshl_or_b32 v124, v216, 9, v215
	v_add_u32_e32 v125, s42, v178
	s_waitcnt lgkmcnt(0)
	s_barrier
	ds_read_b32 v132, v125
	v_lshl_add_u32 v124, v124, 2, s41
	v_lshlrev_b32_e32 v160, 3, v214
	s_movk_i32 s24, 0xe800
	s_waitcnt lgkmcnt(0)
	v_add_f32_e32 v64, v64, v132
	v_fmamk_f32 v64, v64, 0x3b800000, v203
	v_rsq_f32_e32 v64, v64
	s_nop 0
	v_mul_f32_e32 v64, v212, v64
	v_mul_f32_e32 v106, v106, v64
	v_mul_f32_e32 v108, v108, v64
	ds_write2_b32 v124, v106, v108 offset1:32
	v_mul_f32_e32 v106, v114, v64
	v_mul_f32_e32 v64, v122, v64
	ds_write2_b32 v124, v106, v64 offset0:64 offset1:96
	ds_read_b32 v64, v125 offset:4
	s_waitcnt lgkmcnt(0)
	v_add_f32_e32 v64, v65, v64
	v_fmamk_f32 v64, v64, 0x3b800000, v203
	v_rsq_f32_e32 v64, v64
	s_nop 0
	v_mul_f32_e32 v64, v212, v64
	v_mul_f32_e32 v65, v107, v64
	v_mul_f32_e32 v106, v109, v64
	v_mul_f32_e32 v107, v115, v64
	v_mul_f32_e32 v64, v123, v64
	ds_write2_b32 v124, v65, v106 offset0:128 offset1:160
	ds_write2_b32 v124, v107, v64 offset0:192 offset1:224
	ds_read_b32 v64, v125 offset:8
	v_add_u32_e32 v65, 0x400, v124
	s_waitcnt lgkmcnt(0)
	v_add_f32_e32 v64, v66, v64
	v_fmamk_f32 v64, v64, 0x3b800000, v203
	v_rsq_f32_e32 v64, v64
	s_nop 0
	v_mul_f32_e32 v64, v212, v64
	v_mul_f32_e32 v66, v118, v64
	v_mul_f32_e32 v106, v120, v64
	v_mul_f32_e32 v107, v166, v64
	v_mul_f32_e32 v64, v168, v64
	ds_write2_b32 v65, v66, v106 offset1:32
	ds_write2_b32 v65, v107, v64 offset0:64 offset1:96
	ds_read_b32 v64, v125 offset:12
	s_waitcnt lgkmcnt(0)
	v_add_f32_e32 v64, v67, v64
	v_fmamk_f32 v64, v64, 0x3b800000, v203
	v_rsq_f32_e32 v64, v64
	s_nop 0
	v_mul_f32_e32 v64, v212, v64
	v_mul_f32_e32 v66, v119, v64
	v_mul_f32_e32 v67, v121, v64
	v_mul_f32_e32 v106, v167, v64
	v_mul_f32_e32 v64, v169, v64
	ds_write2_b32 v65, v66, v67 offset0:128 offset1:160
	ds_write2_b32 v65, v106, v64 offset0:192 offset1:224
	ds_read_b32 v64, v125 offset:32
	v_add_u32_e32 v65, 0x1000, v124
	s_waitcnt lgkmcnt(0)
; __device__ __forceinline__ unsigned cvtpk2(float lo, float hi) { return __builtin_bit_cast(unsigned, __builtin_convertvector((f32x2){lo, hi}, bf16v2)); }
; __device__ __forceinline__ float bf2f(bf16_t b) { return __uint_as_float((unsigned)b << 16); }
; __device__ __forceinline__ float silu_f(float z) { return z * __builtin_amdgcn_rcpf(1.f + __builtin_amdgcn_exp2f(-1.4426950408889634f * z)); }
; template <int LD> ...
;     ...
;   float* stg = (float*)(lds + wv * 16384);
;   unsigned wb = (unsigned)(4 * hi * 128 + r32); asm volatile("" : "+v"(wb));
; #pragma unroll
;   for (int r = 0; r < 16; ++r) { const unsigned cr = (r & 3) + 8 * (r >> 2);
;     const float rs = __builtin_amdgcn_rsqf((ss[r] + xs[(wv ^ 1) * 32 + cr + 4 * hi]) * (1.f / 256.f) + EPS) * epi.oscale;
; #pragma unroll
;     for (int d0 = 0; d0 < 4; ++d0) stg[wb + cr * 128 + d0 * 32] = o[d0][r] * rs; }
;   unsigned rr = (unsigned)(lane >> 4), c8 = (unsigned)(lane & 15) * 8; asm volatile("" : "+v"(rr), "+v"(c8));
;   const unsigned zb = (unsigned)(rb * QBLK + rr) * LD + kh * 128 + c8, ob = (unsigned)(rb * QBLK + rr) * DM + kh * 128 + c8, sb = rr * 128 + c8;
;   const f32x4 sg0 = *(const f32x4*)(epi.sg + kh * 128 + c8), sg1 = *(const f32x4*)(epi.sg + kh * 128 + c8 + 4);
; #pragma unroll
;   for (int i = 0; i < 8; ++i) {
;     const f32x4 a = *(const f32x4*)(stg + sb + i * 512), b = *(const f32x4*)(stg + sb + i * 512 + 4);
;     const bf16x8 zz = *(const bf16x8*)(epi.z0 + zb + (unsigned)(i * 4) * LD);
;     float g[8];
; #pragma unroll
;     for (int k = 0; k < 8; ++k) g[k] = silu_f(bf2f((bf16_t)zz[k]));
;     u32x4 w; w.x = cvtpk2(a[0] * sg0[0] * g[0], a[1] * sg0[1] * g[1]); w.y = cvtpk2(a[2] * sg0[2] * g[2], a[3] * sg0[3] * g[3]);
;     w.z = cvtpk2(b[0] * sg1[0] * g[4], b[1] * sg1[1] * g[5]); w.w = cvtpk2(b[2] * sg1[2] * g[6], b[3] * sg1[3] * g[7]);
;     *(u32x4*)(epi.ao0 + ob + (unsigned)(i * 4) * DM) = w; }
	v_add_f32_e32 v64, v72, v64
	v_fmamk_f32 v64, v64, 0x3b800000, v203
	v_rsq_f32_e32 v64, v64
	s_nop 0
	v_mul_f32_e32 v64, v212, v64
	v_mul_f32_e32 v66, v150, v64
	v_mul_f32_e32 v67, v152, v64
	v_mul_f32_e32 v72, v170, v64
	v_mul_f32_e32 v64, v172, v64
	ds_write2_b32 v65, v66, v67 offset1:32
	ds_write2_b32 v65, v72, v64 offset0:64 offset1:96
	ds_read_b32 v64, v125 offset:36
	s_waitcnt lgkmcnt(0)
	v_add_f32_e32 v64, v73, v64
	v_fmamk_f32 v64, v64, 0x3b800000, v203
	v_rsq_f32_e32 v64, v64
	s_nop 0
	v_mul_f32_e32 v64, v212, v64
	v_mul_f32_e32 v66, v151, v64
	v_mul_f32_e32 v67, v153, v64
	v_mul_f32_e32 v72, v171, v64
	v_mul_f32_e32 v64, v173, v64
	ds_write2_b32 v65, v66, v67 offset0:128 offset1:160
	ds_write2_b32 v65, v72, v64 offset0:192 offset1:224
	ds_read_b32 v64, v125 offset:40
	v_add_u32_e32 v65, 0x1400, v124
	s_waitcnt lgkmcnt(0)
	v_add_f32_e32 v64, v74, v64
	v_fmamk_f32 v64, v64, 0x3b800000, v203
	v_rsq_f32_e32 v64, v64
	s_nop 0
	v_mul_f32_e32 v64, v212, v64
	v_mul_f32_e32 v66, v138, v64
	v_mul_f32_e32 v67, v140, v64
	v_mul_f32_e32 v72, v154, v64
	v_mul_f32_e32 v64, v156, v64
	ds_write2_b32 v65, v66, v67 offset1:32
	ds_write2_b32 v65, v72, v64 offset0:64 offset1:96
	ds_read_b32 v64, v125 offset:44
	s_waitcnt lgkmcnt(0)
	v_add_f32_e32 v64, v75, v64
	v_fmamk_f32 v64, v64, 0x3b800000, v203
	v_rsq_f32_e32 v64, v64
	s_nop 0
	v_mul_f32_e32 v64, v212, v64
	v_mul_f32_e32 v66, v139, v64
	v_mul_f32_e32 v67, v141, v64
	v_mul_f32_e32 v72, v155, v64
	v_mul_f32_e32 v64, v157, v64
	ds_write2_b32 v65, v66, v67 offset0:128 offset1:160
	ds_write2_b32 v65, v72, v64 offset0:192 offset1:224
	ds_read_b32 v64, v125 offset:64
	v_add_u32_e32 v65, 0x2000, v124
	s_waitcnt lgkmcnt(0)
	v_add_f32_e32 v64, v76, v64
	v_fmamk_f32 v64, v64, 0x3b800000, v203
	v_rsq_f32_e32 v64, v64
	s_nop 0
	v_mul_f32_e32 v64, v212, v64
	v_mul_f32_e32 v66, v130, v64
	v_mul_f32_e32 v67, v144, v64
	v_mul_f32_e32 v72, v146, v64
	v_mul_f32_e32 v64, v158, v64
	ds_write2_b32 v65, v66, v67 offset1:32
	ds_write2_b32 v65, v72, v64 offset0:64 offset1:96
	ds_read_b32 v64, v125 offset:68
	s_waitcnt lgkmcnt(0)
	v_add_f32_e32 v64, v77, v64
	v_fmamk_f32 v64, v64, 0x3b800000, v203
	v_rsq_f32_e32 v64, v64
	s_nop 0
	v_mul_f32_e32 v64, v212, v64
	v_mul_f32_e32 v66, v131, v64
	v_mul_f32_e32 v67, v145, v64
	v_mul_f32_e32 v72, v147, v64
	v_mul_f32_e32 v64, v159, v64
	ds_write2_b32 v65, v66, v67 offset0:128 offset1:160
	ds_write2_b32 v65, v72, v64 offset0:192 offset1:224
	ds_read_b32 v64, v125 offset:72
	v_add_u32_e32 v65, 0x2400, v124
	s_waitcnt lgkmcnt(0)
	v_add_f32_e32 v64, v78, v64
	v_fmamk_f32 v64, v64, 0x3b800000, v203
	v_rsq_f32_e32 v64, v64
	s_nop 0
	v_mul_f32_e32 v64, v212, v64
	v_mul_f32_e32 v66, v116, v64
	v_mul_f32_e32 v67, v134, v64
	v_mul_f32_e32 v72, v136, v64
	v_mul_f32_e32 v64, v142, v64
	ds_write2_b32 v65, v66, v67 offset1:32
	ds_write2_b32 v65, v72, v64 offset0:64 offset1:96
	ds_read_b32 v64, v125 offset:76
	s_waitcnt lgkmcnt(0)
	v_add_f32_e32 v64, v79, v64
	v_fmamk_f32 v64, v64, 0x3b800000, v203
	v_rsq_f32_e32 v64, v64
	s_nop 0
	v_mul_f32_e32 v64, v212, v64
	v_mul_f32_e32 v66, v117, v64
	v_mul_f32_e32 v67, v135, v64
	v_mul_f32_e32 v72, v137, v64
	v_mul_f32_e32 v64, v143, v64
	ds_write2_b32 v65, v66, v67 offset0:128 offset1:160
	ds_write2_b32 v65, v72, v64 offset0:192 offset1:224
	ds_read_b32 v64, v125 offset:96
	v_add_u32_e32 v65, 0x3000, v124
	s_waitcnt lgkmcnt(0)
	v_add_f32_e32 v64, v68, v64
	v_fmamk_f32 v64, v64, 0x3b800000, v203
	v_rsq_f32_e32 v64, v64
	s_nop 0
	v_mul_f32_e32 v64, v212, v64
	v_mul_f32_e32 v66, v102, v64
	v_mul_f32_e32 v67, v104, v64
	v_mul_f32_e32 v68, v126, v64
	v_mul_f32_e32 v64, v128, v64
	ds_write2_b32 v65, v66, v67 offset1:32
	ds_write2_b32 v65, v68, v64 offset0:64 offset1:96
	ds_read_b32 v64, v125 offset:100
	s_waitcnt lgkmcnt(0)
	v_add_f32_e32 v64, v69, v64
	v_fmamk_f32 v64, v64, 0x3b800000, v203
	v_rsq_f32_e32 v64, v64
	s_nop 0
	v_mul_f32_e32 v64, v212, v64
	v_mul_f32_e32 v66, v103, v64
	v_mul_f32_e32 v67, v105, v64
	v_mul_f32_e32 v68, v127, v64
	v_mul_f32_e32 v64, v129, v64
	ds_write2_b32 v65, v66, v67 offset0:128 offset1:160
	ds_write2_b32 v65, v68, v64 offset0:192 offset1:224
	ds_read_b32 v64, v125 offset:104
	v_add_u32_e32 v65, 0x3400, v124
	s_waitcnt lgkmcnt(0)
	v_add_f32_e32 v64, v70, v64
	v_fmamk_f32 v64, v64, 0x3b800000, v203
	v_rsq_f32_e32 v64, v64
	s_nop 0
	v_mul_f32_e32 v64, v212, v64
	v_mul_f32_e32 v66, v98, v64
	v_mul_f32_e32 v67, v100, v64
	v_mul_f32_e32 v68, v110, v64
	v_mul_f32_e32 v64, v112, v64
	ds_write2_b32 v65, v66, v67 offset1:32
	ds_write2_b32 v65, v68, v64 offset0:64 offset1:96
	ds_read_b32 v64, v125 offset:108
	s_waitcnt lgkmcnt(0)
	v_add_f32_e32 v64, v71, v64
	v_fmamk_f32 v64, v64, 0x3b800000, v203
	v_rsq_f32_e32 v64, v64
	s_nop 0
	v_mul_f32_e32 v64, v212, v64
	v_mul_f32_e32 v66, v99, v64
	v_mul_f32_e32 v67, v101, v64
	v_mul_f32_e32 v68, v111, v64
	v_mul_f32_e32 v64, v113, v64
	ds_write2_b32 v65, v66, v67 offset0:128 offset1:160
	ds_write2_b32 v65, v68, v64 offset0:192 offset1:224
	s_nop 0
	v_add_u32_e32 v73, s36, v213
	v_add_u32_e32 v64, s43, v160
	v_lshl_add_u32 v72, v73, 13, v64
	v_mad_u64_u32 v[78:79], s[24:25], v73, s24, v[72:73]
	v_mov_b32_e32 v73, v161
	v_lshl_add_u64 v[68:69], v[160:161], 2, s[10:11]
	v_lshl_add_u64 v[74:75], v[72:73], 1, s[22:23]
	global_load_dwordx4 v[64:67], v[68:69], off offset:16
	s_nop 0
	global_load_dwordx4 v[68:71], v[68:69], off
	v_lshlrev_b32_e32 v72, 9, v213
	global_load_dwordx4 v[182:185], v[74:75], off
	v_mov_b32_e32 v250, 0x10000
	v_mov_b32_e32 v251, 0
	v_lshl_add_u64 v[254:255], v[74:75], 0, v[250:251]
	global_load_dwordx4 v[186:189], v[254:255], off
	v_lshl_add_u64 v[254:255], v[254:255], 0, v[250:251]
	global_load_dwordx4 v[190:193], v[254:255], off
	v_lshl_add_u64 v[254:255], v[254:255], 0, v[250:251]
	global_load_dwordx4 v[194:197], v[254:255], off
	v_lshl_add_u64 v[254:255], v[254:255], 0, v[250:251]
	global_load_dwordx4 v[198:201], v[254:255], off
	v_lshl_add_u64 v[254:255], v[254:255], 0, v[250:251]
	global_load_dwordx4 v[220:223], v[254:255], off
	v_lshl_add_u64 v[254:255], v[254:255], 0, v[250:251]
	global_load_dwordx4 v[224:227], v[254:255], off
	v_lshl_add_u64 v[254:255], v[254:255], 0, v[250:251]
	global_load_dwordx4 v[228:231], v[254:255], off
	v_lshlrev_b32_e32 v73, 2, v160
	v_add3_u32 v76, s41, v72, v73
	ds_read_b128 v[102:105], v76
	ds_read_b128 v[106:109], v76 offset:16
	v_mov_b32_e32 v79, v161
	v_lshl_add_u64 v[72:73], v[78:79], 1, s[16:17]
	v_add_co_u32_e32 v78, vcc, s65, v74
	s_mov_b32 s24, 0x30000
	s_nop 0
	v_addc_co_u32_e32 v79, vcc, 0, v75, vcc
	s_waitcnt lgkmcnt(0)
; __device__ __forceinline__ unsigned cvtpk2(float lo, float hi) { return __builtin_bit_cast(unsigned, __builtin_convertvector((f32x2){lo, hi}, bf16v2)); }
; __device__ __forceinline__ float bf2f(bf16_t b) { return __uint_as_float((unsigned)b << 16); }
; __device__ __forceinline__ float silu_f(float z) { return z * __builtin_amdgcn_rcpf(1.f + __builtin_amdgcn_exp2f(-1.4426950408889634f * z)); }
; template <int LD> ...
;     ...
;   for (int i = 0; i < 8; ++i) {
;     const f32x4 a = *(const f32x4*)(stg + sb + i * 512), b = *(const f32x4*)(stg + sb + i * 512 + 4);
;     const bf16x8 zz = *(const bf16x8*)(epi.z0 + zb + (unsigned)(i * 4) * LD);
;     float g[8];
; #pragma unroll
;     for (int k = 0; k < 8; ++k) g[k] = silu_f(bf2f((bf16_t)zz[k]));
;     u32x4 w; w.x = cvtpk2(a[0] * sg0[0] * g[0], a[1] * sg0[1] * g[1]); w.y = cvtpk2(a[2] * sg0[2] * g[2], a[3] * sg0[3] * g[3]);
;     w.z = cvtpk2(b[0] * sg1[0] * g[4], b[1] * sg1[1] * g[5]); w.w = cvtpk2(b[2] * sg1[2] * g[6], b[3] * sg1[3] * g[7]);
;     *(u32x4*)(epi.ao0 + ob + (unsigned)(i * 4) * DM) = w; }
	s_waitcnt vmcnt(9)
	v_pk_mul_f32 v[108:109], v[66:67], v[108:109]
	s_waitcnt vmcnt(8)
	v_pk_mul_f32 v[104:105], v[70:71], v[104:105]
	v_pk_mul_f32 v[102:103], v[68:69], v[102:103]
	s_waitcnt vmcnt(7)
	v_and_b32_e32 v111, 0xffff0000, v182
	v_lshlrev_b32_e32 v110, 16, v182
	v_and_b32_e32 v113, 0xffff0000, v183
	v_lshlrev_b32_e32 v112, 16, v183
	v_and_b32_e32 v99, 0xffff0000, v184
	v_lshlrev_b32_e32 v98, 16, v184
	v_and_b32_e32 v115, 0xffff0000, v185
	v_lshlrev_b32_e32 v114, 16, v185
	v_mul_f32_e32 v77, 0xbfb8aa3b, v110
	v_mul_f32_e32 v100, 0xbfb8aa3b, v111
	v_mul_f32_e32 v101, 0xbfb8aa3b, v112
	v_mul_f32_e32 v116, 0xbfb8aa3b, v113
	v_mul_f32_e32 v117, 0xbfb8aa3b, v98
	v_mul_f32_e32 v118, 0xbfb8aa3b, v99
	v_mul_f32_e32 v119, 0xbfb8aa3b, v114
	v_mul_f32_e32 v120, 0xbfb8aa3b, v115
	v_exp_f32_e32 v77, v77
	v_exp_f32_e32 v100, v100
	v_exp_f32_e32 v101, v101
	v_exp_f32_e32 v116, v116
	v_exp_f32_e32 v117, v117
	v_exp_f32_e32 v118, v118
	v_exp_f32_e32 v119, v119
	v_exp_f32_e32 v120, v120
	v_add_f32_e32 v77, 1.0, v77
	v_add_f32_e32 v121, 1.0, v100
	v_add_f32_e32 v122, 1.0, v101
	v_add_f32_e32 v123, 1.0, v116
	v_add_f32_e32 v124, 1.0, v117
	v_add_f32_e32 v125, 1.0, v118
	v_add_f32_e32 v126, 1.0, v119
	v_add_f32_e32 v127, 1.0, v120
	v_rcp_f32_e32 v100, v77
	v_rcp_f32_e32 v101, v121
	v_rcp_f32_e32 v116, v122
	v_rcp_f32_e32 v117, v123
	v_rcp_f32_e32 v118, v124
	v_rcp_f32_e32 v119, v125
	v_rcp_f32_e32 v120, v126
	v_rcp_f32_e32 v121, v127
	v_pk_mul_f32 v[106:107], v[64:65], v[106:107]
	v_pk_mul_f32 v[100:101], v[100:101], v[110:111]
	v_pk_mul_f32 v[110:111], v[116:117], v[112:113]
	v_pk_mul_f32 v[98:99], v[118:119], v[98:99]
	v_pk_mul_f32 v[112:113], v[120:121], v[114:115]
	v_pk_mul_f32 v[100:101], v[102:103], v[100:101]
	v_pk_mul_f32 v[102:103], v[104:105], v[110:111]
	v_pk_mul_f32 v[104:105], v[106:107], v[98:99]
	v_pk_mul_f32 v[106:107], v[108:109], v[112:113]
	v_cvt_pk_bf16_f32 v98, v100, v101
	v_cvt_pk_bf16_f32 v99, v102, v103
	v_cvt_pk_bf16_f32 v100, v104, v105
	v_cvt_pk_bf16_f32 v101, v106, v107
	global_store_dwordx4 v[72:73], v[98:101], off
	ds_read_b128 v[102:105], v76 offset:2048
	ds_read_b128 v[106:109], v76 offset:2064
	v_add_co_u32_e32 v78, vcc, s64, v74
	s_waitcnt lgkmcnt(1)
	v_pk_mul_f32 v[104:105], v[70:71], v[104:105]
	v_addc_co_u32_e32 v79, vcc, 0, v75, vcc
	v_pk_mul_f32 v[102:103], v[68:69], v[102:103]
	s_waitcnt lgkmcnt(0)
	v_pk_mul_f32 v[108:109], v[66:67], v[108:109]
	v_pk_mul_f32 v[106:107], v[64:65], v[106:107]
	v_add_co_u32_e32 v110, vcc, s93, v72
	s_waitcnt vmcnt(7)
	v_and_b32_e32 v113, 0xffff0000, v186
	v_lshlrev_b32_e32 v112, 16, v186
	v_and_b32_e32 v115, 0xffff0000, v187
	v_lshlrev_b32_e32 v114, 16, v187
	v_and_b32_e32 v99, 0xffff0000, v188
	v_lshlrev_b32_e32 v98, 16, v188
	v_and_b32_e32 v117, 0xffff0000, v189
	v_lshlrev_b32_e32 v116, 16, v189
	v_mul_f32_e32 v77, 0xbfb8aa3b, v112
	v_mul_f32_e32 v100, 0xbfb8aa3b, v113
	v_mul_f32_e32 v101, 0xbfb8aa3b, v114
	v_mul_f32_e32 v118, 0xbfb8aa3b, v115
	v_mul_f32_e32 v119, 0xbfb8aa3b, v98
	v_mul_f32_e32 v120, 0xbfb8aa3b, v99
	v_mul_f32_e32 v121, 0xbfb8aa3b, v116
	v_mul_f32_e32 v122, 0xbfb8aa3b, v117
	v_exp_f32_e32 v77, v77
	v_exp_f32_e32 v100, v100
	v_exp_f32_e32 v101, v101
	v_exp_f32_e32 v118, v118
	v_exp_f32_e32 v119, v119
	v_exp_f32_e32 v120, v120
	v_exp_f32_e32 v121, v121
	v_exp_f32_e32 v122, v122
	v_add_f32_e32 v77, 1.0, v77
	v_add_f32_e32 v123, 1.0, v100
	v_add_f32_e32 v124, 1.0, v101
	v_add_f32_e32 v125, 1.0, v118
	v_add_f32_e32 v126, 1.0, v119
	v_add_f32_e32 v127, 1.0, v120
	v_add_f32_e32 v128, 1.0, v121
	v_add_f32_e32 v129, 1.0, v122
	v_rcp_f32_e32 v100, v77
	v_rcp_f32_e32 v101, v123
	v_rcp_f32_e32 v118, v124
	v_rcp_f32_e32 v119, v125
	v_rcp_f32_e32 v120, v126
	v_rcp_f32_e32 v121, v127
	v_rcp_f32_e32 v122, v128
	v_rcp_f32_e32 v123, v129
	v_pk_mul_f32 v[100:101], v[100:101], v[112:113]
	v_pk_mul_f32 v[112:113], v[118:119], v[114:115]
	v_pk_mul_f32 v[98:99], v[120:121], v[98:99]
	v_pk_mul_f32 v[114:115], v[122:123], v[116:117]
	v_pk_mul_f32 v[100:101], v[102:103], v[100:101]
	v_pk_mul_f32 v[102:103], v[104:105], v[112:113]
	v_pk_mul_f32 v[104:105], v[106:107], v[98:99]
	v_pk_mul_f32 v[106:107], v[108:109], v[114:115]
	v_addc_co_u32_e32 v111, vcc, 0, v73, vcc
	v_cvt_pk_bf16_f32 v98, v100, v101
	v_cvt_pk_bf16_f32 v99, v102, v103
	v_cvt_pk_bf16_f32 v100, v104, v105
	v_cvt_pk_bf16_f32 v101, v106, v107
	global_store_dwordx4 v[110:111], v[98:101], off
	ds_read_b128 v[102:105], v76 offset:4096
	ds_read_b128 v[106:109], v76 offset:4112
	v_add_co_u32_e32 v78, vcc, s24, v74
	s_mov_b32 s24, 0x40000
	s_nop 0
	v_addc_co_u32_e32 v79, vcc, 0, v75, vcc
	s_waitcnt lgkmcnt(1)
	v_pk_mul_f32 v[104:105], v[70:71], v[104:105]
	v_pk_mul_f32 v[102:103], v[68:69], v[102:103]
	s_waitcnt lgkmcnt(0)
	v_pk_mul_f32 v[108:109], v[66:67], v[108:109]
	v_pk_mul_f32 v[106:107], v[64:65], v[106:107]
	v_add_co_u32_e32 v110, vcc, s66, v72
	s_waitcnt vmcnt(7)
; __device__ __forceinline__ unsigned cvtpk2(float lo, float hi) { return __builtin_bit_cast(unsigned, __builtin_convertvector((f32x2){lo, hi}, bf16v2)); }
; __device__ __forceinline__ float bf2f(bf16_t b) { return __uint_as_float((unsigned)b << 16); }
; __device__ __forceinline__ float silu_f(float z) { return z * __builtin_amdgcn_rcpf(1.f + __builtin_amdgcn_exp2f(-1.4426950408889634f * z)); }
; template <int LD> ...
;     ...
;   for (int i = 0; i < 8; ++i) {
;     const f32x4 a = *(const f32x4*)(stg + sb + i * 512), b = *(const f32x4*)(stg + sb + i * 512 + 4);
;     const bf16x8 zz = *(const bf16x8*)(epi.z0 + zb + (unsigned)(i * 4) * LD);
;     float g[8];
; #pragma unroll
;     for (int k = 0; k < 8; ++k) g[k] = silu_f(bf2f((bf16_t)zz[k]));
;     u32x4 w; w.x = cvtpk2(a[0] * sg0[0] * g[0], a[1] * sg0[1] * g[1]); w.y = cvtpk2(a[2] * sg0[2] * g[2], a[3] * sg0[3] * g[3]);
;     w.z = cvtpk2(b[0] * sg1[0] * g[4], b[1] * sg1[1] * g[5]); w.w = cvtpk2(b[2] * sg1[2] * g[6], b[3] * sg1[3] * g[7]);
;     *(u32x4*)(epi.ao0 + ob + (unsigned)(i * 4) * DM) = w; }
	v_and_b32_e32 v113, 0xffff0000, v190
	v_lshlrev_b32_e32 v112, 16, v190
	v_and_b32_e32 v115, 0xffff0000, v191
	v_lshlrev_b32_e32 v114, 16, v191
	v_and_b32_e32 v99, 0xffff0000, v192
	v_lshlrev_b32_e32 v98, 16, v192
	v_and_b32_e32 v117, 0xffff0000, v193
	v_lshlrev_b32_e32 v116, 16, v193
	v_mul_f32_e32 v77, 0xbfb8aa3b, v112
	v_mul_f32_e32 v100, 0xbfb8aa3b, v113
	v_mul_f32_e32 v101, 0xbfb8aa3b, v114
	v_mul_f32_e32 v118, 0xbfb8aa3b, v115
	v_mul_f32_e32 v119, 0xbfb8aa3b, v98
	v_mul_f32_e32 v120, 0xbfb8aa3b, v99
	v_mul_f32_e32 v121, 0xbfb8aa3b, v116
	v_mul_f32_e32 v122, 0xbfb8aa3b, v117
	v_exp_f32_e32 v77, v77
	v_exp_f32_e32 v100, v100
	v_exp_f32_e32 v101, v101
	v_exp_f32_e32 v118, v118
	v_exp_f32_e32 v119, v119
	v_exp_f32_e32 v120, v120
	v_exp_f32_e32 v121, v121
	v_exp_f32_e32 v122, v122
	v_add_f32_e32 v77, 1.0, v77
	v_add_f32_e32 v123, 1.0, v100
	v_add_f32_e32 v124, 1.0, v101
	v_add_f32_e32 v125, 1.0, v118
	v_add_f32_e32 v126, 1.0, v119
	v_add_f32_e32 v127, 1.0, v120
	v_add_f32_e32 v128, 1.0, v121
	v_add_f32_e32 v129, 1.0, v122
	v_rcp_f32_e32 v100, v77
	v_rcp_f32_e32 v101, v123
	v_rcp_f32_e32 v118, v124
	v_rcp_f32_e32 v119, v125
	v_rcp_f32_e32 v120, v126
	v_rcp_f32_e32 v121, v127
	v_rcp_f32_e32 v122, v128
	v_rcp_f32_e32 v123, v129
	v_pk_mul_f32 v[100:101], v[100:101], v[112:113]
	v_pk_mul_f32 v[112:113], v[118:119], v[114:115]
	v_pk_mul_f32 v[98:99], v[120:121], v[98:99]
	v_pk_mul_f32 v[114:115], v[122:123], v[116:117]
	v_pk_mul_f32 v[100:101], v[102:103], v[100:101]
	v_pk_mul_f32 v[102:103], v[104:105], v[112:113]
	v_pk_mul_f32 v[104:105], v[106:107], v[98:99]
	v_pk_mul_f32 v[106:107], v[108:109], v[114:115]
	v_addc_co_u32_e32 v111, vcc, 0, v73, vcc
	v_cvt_pk_bf16_f32 v98, v100, v101
	v_cvt_pk_bf16_f32 v99, v102, v103
	v_cvt_pk_bf16_f32 v100, v104, v105
	v_cvt_pk_bf16_f32 v101, v106, v107
	global_store_dwordx4 v[110:111], v[98:101], off
	ds_read_b128 v[102:105], v76 offset:6144
	ds_read_b128 v[106:109], v76 offset:6160
	v_add_co_u32_e32 v78, vcc, s24, v74
	s_mov_b32 s24, 0x50000
	s_nop 0
	v_addc_co_u32_e32 v79, vcc, 0, v75, vcc
	s_waitcnt lgkmcnt(1)
	v_pk_mul_f32 v[104:105], v[70:71], v[104:105]
	v_pk_mul_f32 v[102:103], v[68:69], v[102:103]
	s_waitcnt lgkmcnt(0)
	v_pk_mul_f32 v[108:109], v[66:67], v[108:109]
	v_pk_mul_f32 v[106:107], v[64:65], v[106:107]
	v_add_co_u32_e32 v110, vcc, s95, v72
	s_waitcnt vmcnt(7)
	v_and_b32_e32 v113, 0xffff0000, v194
	v_lshlrev_b32_e32 v112, 16, v194
	v_and_b32_e32 v115, 0xffff0000, v195
	v_lshlrev_b32_e32 v114, 16, v195
	v_and_b32_e32 v99, 0xffff0000, v196
	v_lshlrev_b32_e32 v98, 16, v196
	v_and_b32_e32 v117, 0xffff0000, v197
	v_lshlrev_b32_e32 v116, 16, v197
	v_mul_f32_e32 v77, 0xbfb8aa3b, v112
	v_mul_f32_e32 v100, 0xbfb8aa3b, v113
	v_mul_f32_e32 v101, 0xbfb8aa3b, v114
	v_mul_f32_e32 v118, 0xbfb8aa3b, v115
	v_mul_f32_e32 v119, 0xbfb8aa3b, v98
	v_mul_f32_e32 v120, 0xbfb8aa3b, v99
	v_mul_f32_e32 v121, 0xbfb8aa3b, v116
	v_mul_f32_e32 v122, 0xbfb8aa3b, v117
	v_exp_f32_e32 v77, v77
	v_exp_f32_e32 v100, v100
	v_exp_f32_e32 v101, v101
	v_exp_f32_e32 v118, v118
	v_exp_f32_e32 v119, v119
	v_exp_f32_e32 v120, v120
	v_exp_f32_e32 v121, v121
	v_exp_f32_e32 v122, v122
	v_add_f32_e32 v77, 1.0, v77
	v_add_f32_e32 v123, 1.0, v100
	v_add_f32_e32 v124, 1.0, v101
	v_add_f32_e32 v125, 1.0, v118
	v_add_f32_e32 v126, 1.0, v119
	v_add_f32_e32 v127, 1.0, v120
	v_add_f32_e32 v128, 1.0, v121
	v_add_f32_e32 v129, 1.0, v122
	v_rcp_f32_e32 v100, v77
	v_rcp_f32_e32 v101, v123
	v_rcp_f32_e32 v118, v124
	v_rcp_f32_e32 v119, v125
	v_rcp_f32_e32 v120, v126
	v_rcp_f32_e32 v121, v127
	v_rcp_f32_e32 v122, v128
	v_rcp_f32_e32 v123, v129
	v_pk_mul_f32 v[100:101], v[100:101], v[112:113]
	v_pk_mul_f32 v[112:113], v[118:119], v[114:115]
	v_pk_mul_f32 v[98:99], v[120:121], v[98:99]
	v_pk_mul_f32 v[114:115], v[122:123], v[116:117]
	v_pk_mul_f32 v[100:101], v[102:103], v[100:101]
	v_pk_mul_f32 v[102:103], v[104:105], v[112:113]
	v_pk_mul_f32 v[104:105], v[106:107], v[98:99]
	v_pk_mul_f32 v[106:107], v[108:109], v[114:115]
	v_addc_co_u32_e32 v111, vcc, 0, v73, vcc
	v_cvt_pk_bf16_f32 v98, v100, v101
	v_cvt_pk_bf16_f32 v99, v102, v103
	v_cvt_pk_bf16_f32 v100, v104, v105
	v_cvt_pk_bf16_f32 v101, v106, v107
	global_store_dwordx4 v[110:111], v[98:101], off
	ds_read_b128 v[102:105], v76 offset:8192
	ds_read_b128 v[106:109], v76 offset:8208
	v_add_co_u32_e32 v78, vcc, s24, v74
	s_mov_b32 s24, 0x60000
	s_nop 0
	v_addc_co_u32_e32 v79, vcc, 0, v75, vcc
	s_waitcnt lgkmcnt(1)
	v_pk_mul_f32 v[104:105], v[70:71], v[104:105]
	v_pk_mul_f32 v[102:103], v[68:69], v[102:103]
	s_waitcnt lgkmcnt(0)
	v_pk_mul_f32 v[108:109], v[66:67], v[108:109]
	v_pk_mul_f32 v[106:107], v[64:65], v[106:107]
	v_add_co_u32_e32 v110, vcc, s65, v72
	s_waitcnt vmcnt(7)
; __device__ __forceinline__ unsigned cvtpk2(float lo, float hi) { return __builtin_bit_cast(unsigned, __builtin_convertvector((f32x2){lo, hi}, bf16v2)); }
; __device__ __forceinline__ float bf2f(bf16_t b) { return __uint_as_float((unsigned)b << 16); }
; __device__ __forceinline__ float silu_f(float z) { return z * __builtin_amdgcn_rcpf(1.f + __builtin_amdgcn_exp2f(-1.4426950408889634f * z)); }
; template <int LD> ...
;     ...
;   for (int i = 0; i < 8; ++i) {
;     const f32x4 a = *(const f32x4*)(stg + sb + i * 512), b = *(const f32x4*)(stg + sb + i * 512 + 4);
;     const bf16x8 zz = *(const bf16x8*)(epi.z0 + zb + (unsigned)(i * 4) * LD);
;     float g[8];
; #pragma unroll
;     for (int k = 0; k < 8; ++k) g[k] = silu_f(bf2f((bf16_t)zz[k]));
;     u32x4 w; w.x = cvtpk2(a[0] * sg0[0] * g[0], a[1] * sg0[1] * g[1]); w.y = cvtpk2(a[2] * sg0[2] * g[2], a[3] * sg0[3] * g[3]);
;     w.z = cvtpk2(b[0] * sg1[0] * g[4], b[1] * sg1[1] * g[5]); w.w = cvtpk2(b[2] * sg1[2] * g[6], b[3] * sg1[3] * g[7]);
;     *(u32x4*)(epi.ao0 + ob + (unsigned)(i * 4) * DM) = w; }
	v_and_b32_e32 v113, 0xffff0000, v198
	v_lshlrev_b32_e32 v112, 16, v198
	v_and_b32_e32 v115, 0xffff0000, v199
	v_lshlrev_b32_e32 v114, 16, v199
	v_and_b32_e32 v99, 0xffff0000, v200
	v_lshlrev_b32_e32 v98, 16, v200
	v_and_b32_e32 v117, 0xffff0000, v201
	v_lshlrev_b32_e32 v116, 16, v201
	v_mul_f32_e32 v77, 0xbfb8aa3b, v112
	v_mul_f32_e32 v100, 0xbfb8aa3b, v113
	v_mul_f32_e32 v101, 0xbfb8aa3b, v114
	v_mul_f32_e32 v118, 0xbfb8aa3b, v115
	v_mul_f32_e32 v119, 0xbfb8aa3b, v98
	v_mul_f32_e32 v120, 0xbfb8aa3b, v99
	v_mul_f32_e32 v121, 0xbfb8aa3b, v116
	v_mul_f32_e32 v122, 0xbfb8aa3b, v117
	v_exp_f32_e32 v77, v77
	v_exp_f32_e32 v100, v100
	v_exp_f32_e32 v101, v101
	v_exp_f32_e32 v118, v118
	v_exp_f32_e32 v119, v119
	v_exp_f32_e32 v120, v120
	v_exp_f32_e32 v121, v121
	v_exp_f32_e32 v122, v122
	v_add_f32_e32 v77, 1.0, v77
	v_add_f32_e32 v123, 1.0, v100
	v_add_f32_e32 v124, 1.0, v101
	v_add_f32_e32 v125, 1.0, v118
	v_add_f32_e32 v126, 1.0, v119
	v_add_f32_e32 v127, 1.0, v120
	v_add_f32_e32 v128, 1.0, v121
	v_add_f32_e32 v129, 1.0, v122
	v_rcp_f32_e32 v100, v77
	v_rcp_f32_e32 v101, v123
	v_rcp_f32_e32 v118, v124
	v_rcp_f32_e32 v119, v125
	v_rcp_f32_e32 v120, v126
	v_rcp_f32_e32 v121, v127
	v_rcp_f32_e32 v122, v128
	v_rcp_f32_e32 v123, v129
	v_pk_mul_f32 v[100:101], v[100:101], v[112:113]
	v_pk_mul_f32 v[112:113], v[118:119], v[114:115]
	v_pk_mul_f32 v[98:99], v[120:121], v[98:99]
	v_pk_mul_f32 v[114:115], v[122:123], v[116:117]
	v_pk_mul_f32 v[100:101], v[102:103], v[100:101]
	v_pk_mul_f32 v[102:103], v[104:105], v[112:113]
	v_pk_mul_f32 v[104:105], v[106:107], v[98:99]
	v_pk_mul_f32 v[106:107], v[108:109], v[114:115]
	v_addc_co_u32_e32 v111, vcc, 0, v73, vcc
	v_cvt_pk_bf16_f32 v98, v100, v101
	v_cvt_pk_bf16_f32 v99, v102, v103
	v_cvt_pk_bf16_f32 v100, v104, v105
	v_cvt_pk_bf16_f32 v101, v106, v107
	global_store_dwordx4 v[110:111], v[98:101], off
	ds_read_b128 v[102:105], v76 offset:10240
	ds_read_b128 v[106:109], v76 offset:10256
	v_add_co_u32_e32 v78, vcc, s24, v74
	s_mov_b32 s24, 0x14000
	s_nop 0
	v_addc_co_u32_e32 v79, vcc, 0, v75, vcc
	s_waitcnt lgkmcnt(1)
	v_pk_mul_f32 v[104:105], v[70:71], v[104:105]
	v_pk_mul_f32 v[102:103], v[68:69], v[102:103]
	s_waitcnt lgkmcnt(0)
	v_pk_mul_f32 v[108:109], v[66:67], v[108:109]
	v_pk_mul_f32 v[106:107], v[64:65], v[106:107]
	v_add_co_u32_e32 v110, vcc, s24, v72
	s_mov_b32 s24, 0x70000
	s_nop 0
	v_addc_co_u32_e32 v111, vcc, 0, v73, vcc
	v_add_co_u32_e32 v74, vcc, s24, v74
	s_mov_b32 s24, 0x18000
	s_nop 0
	v_addc_co_u32_e32 v75, vcc, 0, v75, vcc
	s_waitcnt vmcnt(7)
	v_and_b32_e32 v113, 0xffff0000, v220
	v_lshlrev_b32_e32 v112, 16, v220
	v_and_b32_e32 v115, 0xffff0000, v221
	v_lshlrev_b32_e32 v114, 16, v221
	v_and_b32_e32 v99, 0xffff0000, v222
	v_lshlrev_b32_e32 v98, 16, v222
	v_and_b32_e32 v117, 0xffff0000, v223
	v_lshlrev_b32_e32 v116, 16, v223
	v_mul_f32_e32 v77, 0xbfb8aa3b, v112
	v_mul_f32_e32 v100, 0xbfb8aa3b, v113
	v_mul_f32_e32 v101, 0xbfb8aa3b, v114
	v_mul_f32_e32 v118, 0xbfb8aa3b, v115
	v_mul_f32_e32 v119, 0xbfb8aa3b, v98
	v_mul_f32_e32 v120, 0xbfb8aa3b, v99
	v_mul_f32_e32 v121, 0xbfb8aa3b, v116
	v_mul_f32_e32 v122, 0xbfb8aa3b, v117
	v_exp_f32_e32 v77, v77
	v_exp_f32_e32 v100, v100
	v_exp_f32_e32 v101, v101
	v_exp_f32_e32 v118, v118
	v_exp_f32_e32 v119, v119
	v_exp_f32_e32 v120, v120
	v_exp_f32_e32 v121, v121
	v_exp_f32_e32 v122, v122
	v_add_f32_e32 v77, 1.0, v77
	v_add_f32_e32 v123, 1.0, v100
	v_add_f32_e32 v124, 1.0, v101
	v_add_f32_e32 v125, 1.0, v118
	v_add_f32_e32 v126, 1.0, v119
	v_add_f32_e32 v127, 1.0, v120
	v_add_f32_e32 v128, 1.0, v121
	v_add_f32_e32 v129, 1.0, v122
	v_rcp_f32_e32 v100, v77
	v_rcp_f32_e32 v101, v123
	v_rcp_f32_e32 v118, v124
	v_rcp_f32_e32 v119, v125
	v_rcp_f32_e32 v120, v126
	v_rcp_f32_e32 v121, v127
	v_rcp_f32_e32 v122, v128
	v_rcp_f32_e32 v123, v129
	v_pk_mul_f32 v[100:101], v[100:101], v[112:113]
	v_pk_mul_f32 v[112:113], v[118:119], v[114:115]
	v_pk_mul_f32 v[98:99], v[120:121], v[98:99]
	v_pk_mul_f32 v[114:115], v[122:123], v[116:117]
	v_pk_mul_f32 v[100:101], v[102:103], v[100:101]
	v_pk_mul_f32 v[102:103], v[104:105], v[112:113]
	v_pk_mul_f32 v[104:105], v[106:107], v[98:99]
	v_pk_mul_f32 v[106:107], v[108:109], v[114:115]
	v_cvt_pk_bf16_f32 v98, v100, v101
	v_cvt_pk_bf16_f32 v99, v102, v103
	v_cvt_pk_bf16_f32 v100, v104, v105
	v_cvt_pk_bf16_f32 v101, v106, v107
	global_store_dwordx4 v[110:111], v[98:101], off
	ds_read_b128 v[102:105], v76 offset:12288
	ds_read_b128 v[106:109], v76 offset:12304
	v_add_co_u32_e32 v78, vcc, s24, v72
	s_waitcnt lgkmcnt(1)
; __device__ __forceinline__ unsigned cvtpk2(float lo, float hi) { return __builtin_bit_cast(unsigned, __builtin_convertvector((f32x2){lo, hi}, bf16v2)); }
; __device__ __forceinline__ float bf2f(bf16_t b) { return __uint_as_float((unsigned)b << 16); }
; __device__ __forceinline__ float silu_f(float z) { return z * __builtin_amdgcn_rcpf(1.f + __builtin_amdgcn_exp2f(-1.4426950408889634f * z)); }
; template <int LD> ...
;     ...
;   for (int i = 0; i < 8; ++i) {
;     const f32x4 a = *(const f32x4*)(stg + sb + i * 512), b = *(const f32x4*)(stg + sb + i * 512 + 4);
;     const bf16x8 zz = *(const bf16x8*)(epi.z0 + zb + (unsigned)(i * 4) * LD);
;     float g[8];
; #pragma unroll
;     for (int k = 0; k < 8; ++k) g[k] = silu_f(bf2f((bf16_t)zz[k]));
;     u32x4 w; w.x = cvtpk2(a[0] * sg0[0] * g[0], a[1] * sg0[1] * g[1]); w.y = cvtpk2(a[2] * sg0[2] * g[2], a[3] * sg0[3] * g[3]);
;     w.z = cvtpk2(b[0] * sg1[0] * g[4], b[1] * sg1[1] * g[5]); w.w = cvtpk2(b[2] * sg1[2] * g[6], b[3] * sg1[3] * g[7]);
;     *(u32x4*)(epi.ao0 + ob + (unsigned)(i * 4) * DM) = w; }
;   __syncthreads();
	v_pk_mul_f32 v[104:105], v[70:71], v[104:105]
	v_pk_mul_f32 v[102:103], v[68:69], v[102:103]
	s_waitcnt lgkmcnt(0)
	v_pk_mul_f32 v[108:109], v[66:67], v[108:109]
	v_pk_mul_f32 v[106:107], v[64:65], v[106:107]
	v_addc_co_u32_e32 v79, vcc, 0, v73, vcc
	v_add_co_u32_e32 v72, vcc, 0x1c000, v72
	s_waitcnt vmcnt(7)
	v_and_b32_e32 v111, 0xffff0000, v224
	v_lshlrev_b32_e32 v110, 16, v224
	v_and_b32_e32 v113, 0xffff0000, v225
	v_lshlrev_b32_e32 v112, 16, v225
	v_and_b32_e32 v99, 0xffff0000, v226
	v_lshlrev_b32_e32 v98, 16, v226
	v_and_b32_e32 v115, 0xffff0000, v227
	v_lshlrev_b32_e32 v114, 16, v227
	v_mul_f32_e32 v77, 0xbfb8aa3b, v110
	v_mul_f32_e32 v100, 0xbfb8aa3b, v111
	v_mul_f32_e32 v101, 0xbfb8aa3b, v112
	v_mul_f32_e32 v116, 0xbfb8aa3b, v113
	v_mul_f32_e32 v117, 0xbfb8aa3b, v98
	v_mul_f32_e32 v118, 0xbfb8aa3b, v99
	v_mul_f32_e32 v119, 0xbfb8aa3b, v114
	v_mul_f32_e32 v120, 0xbfb8aa3b, v115
	v_exp_f32_e32 v77, v77
	v_exp_f32_e32 v100, v100
	v_exp_f32_e32 v101, v101
	v_exp_f32_e32 v116, v116
	v_exp_f32_e32 v117, v117
	v_exp_f32_e32 v118, v118
	v_exp_f32_e32 v119, v119
	v_exp_f32_e32 v120, v120
	v_add_f32_e32 v77, 1.0, v77
	v_add_f32_e32 v121, 1.0, v100
	v_add_f32_e32 v122, 1.0, v101
	v_add_f32_e32 v123, 1.0, v116
	v_add_f32_e32 v124, 1.0, v117
	v_add_f32_e32 v125, 1.0, v118
	v_add_f32_e32 v126, 1.0, v119
	v_add_f32_e32 v127, 1.0, v120
	v_rcp_f32_e32 v100, v77
	v_rcp_f32_e32 v101, v121
	v_rcp_f32_e32 v116, v122
	v_rcp_f32_e32 v117, v123
	v_rcp_f32_e32 v118, v124
	v_rcp_f32_e32 v119, v125
	v_rcp_f32_e32 v120, v126
	v_rcp_f32_e32 v121, v127
	v_pk_mul_f32 v[100:101], v[100:101], v[110:111]
	v_pk_mul_f32 v[110:111], v[116:117], v[112:113]
	v_pk_mul_f32 v[98:99], v[118:119], v[98:99]
	v_pk_mul_f32 v[112:113], v[120:121], v[114:115]
	v_pk_mul_f32 v[100:101], v[102:103], v[100:101]
	v_pk_mul_f32 v[102:103], v[104:105], v[110:111]
	v_pk_mul_f32 v[104:105], v[106:107], v[98:99]
	v_pk_mul_f32 v[106:107], v[108:109], v[112:113]
	v_cvt_pk_bf16_f32 v98, v100, v101
	v_cvt_pk_bf16_f32 v99, v102, v103
	v_cvt_pk_bf16_f32 v100, v104, v105
	v_cvt_pk_bf16_f32 v101, v106, v107
	global_store_dwordx4 v[78:79], v[98:101], off
	ds_read_b128 v[102:105], v76 offset:14336
	ds_read_b128 v[74:77], v76 offset:14352
	v_addc_co_u32_e32 v73, vcc, 0, v73, vcc
	s_waitcnt lgkmcnt(1)
	v_pk_mul_f32 v[70:71], v[70:71], v[104:105]
	s_waitcnt lgkmcnt(0)
	v_pk_mul_f32 v[66:67], v[66:67], v[76:77]
	v_pk_mul_f32 v[64:65], v[64:65], v[74:75]
	v_pk_mul_f32 v[68:69], v[68:69], v[102:103]
	s_waitcnt vmcnt(7)
	v_and_b32_e32 v75, 0xffff0000, v228
	v_lshlrev_b32_e32 v74, 16, v228
	v_and_b32_e32 v77, 0xffff0000, v229
	v_lshlrev_b32_e32 v76, 16, v229
	v_and_b32_e32 v79, 0xffff0000, v230
	v_lshlrev_b32_e32 v78, 16, v230
	v_and_b32_e32 v99, 0xffff0000, v231
	v_lshlrev_b32_e32 v98, 16, v231
	v_mul_f32_e32 v100, 0xbfb8aa3b, v74
	v_mul_f32_e32 v101, 0xbfb8aa3b, v75
	v_mul_f32_e32 v102, 0xbfb8aa3b, v76
	v_mul_f32_e32 v103, 0xbfb8aa3b, v77
	v_mul_f32_e32 v104, 0xbfb8aa3b, v78
	v_mul_f32_e32 v105, 0xbfb8aa3b, v79
	v_mul_f32_e32 v106, 0xbfb8aa3b, v98
	v_mul_f32_e32 v107, 0xbfb8aa3b, v99
	v_exp_f32_e32 v100, v100
	v_exp_f32_e32 v101, v101
	v_exp_f32_e32 v102, v102
	v_exp_f32_e32 v103, v103
	v_exp_f32_e32 v104, v104
	v_exp_f32_e32 v105, v105
	v_exp_f32_e32 v106, v106
	v_exp_f32_e32 v107, v107
	v_add_f32_e32 v100, 1.0, v100
	v_add_f32_e32 v101, 1.0, v101
	v_add_f32_e32 v102, 1.0, v102
	v_add_f32_e32 v103, 1.0, v103
	v_add_f32_e32 v104, 1.0, v104
	v_add_f32_e32 v105, 1.0, v105
	v_add_f32_e32 v106, 1.0, v106
	v_add_f32_e32 v107, 1.0, v107
	v_rcp_f32_e32 v100, v100
	v_rcp_f32_e32 v101, v101
	v_rcp_f32_e32 v102, v102
	v_rcp_f32_e32 v103, v103
	v_rcp_f32_e32 v104, v104
	v_rcp_f32_e32 v105, v105
	v_rcp_f32_e32 v106, v106
	v_rcp_f32_e32 v107, v107
	v_pk_mul_f32 v[74:75], v[100:101], v[74:75]
	v_pk_mul_f32 v[76:77], v[102:103], v[76:77]
	v_pk_mul_f32 v[78:79], v[104:105], v[78:79]
	v_pk_mul_f32 v[98:99], v[106:107], v[98:99]
	v_pk_mul_f32 v[68:69], v[68:69], v[74:75]
	v_pk_mul_f32 v[70:71], v[70:71], v[76:77]
	v_pk_mul_f32 v[74:75], v[64:65], v[78:79]
	v_pk_mul_f32 v[76:77], v[66:67], v[98:99]
	v_cvt_pk_bf16_f32 v64, v68, v69
	v_cvt_pk_bf16_f32 v65, v70, v71
	v_cvt_pk_bf16_f32 v66, v74, v75
	v_cvt_pk_bf16_f32 v67, v76, v77
	global_store_dwordx4 v[72:73], v[64:67], off
	s_barrier
	s_branch .LBB0_20
